# cmb1 + late queue-pop prefetch (B2) + bfe/and attention masks
# baseline (speedup 1.0000x reference)
; DI int pop_block(int* ctr, int*) {
;   __syncthreads();
;   if (threadIdx.x == 0) sh_item = atomicAdd(ctr, 1);
;   __syncthreads();
;   return __builtin_amdgcn_readfirstlane(sh_item);
; }
; DI void phase_b2(const Params& p, int layer, char*, int*) {
;   int* ctr = (int*)(p.ws + W_CTR) + layer * 4 + 1;
;   for (;;) {
;     int it = pop_block(ctr, nullptr);
;     if (it >= N_LRU2) break;
;     if (it < NB_P * NTILE_P * 8) { int sq = it / (NTILE_P * 8), rem = it % (NTILE_P * 8); lru_tile(p, layer, 1, sq, rem >> 3, rem & 7, 1, smem); }
;     else { int j = it - NB_P * NTILE_P * 8; lru_tile(p, layer, 0, j >> 3, 0, j & 7, 1, smem); }
;   }
.LBB0_4489:
	s_barrier
	s_and_saveexec_b64 s[0:1], s[96:97]
	s_cbranch_execz .LBB0_4493
	v_readfirstlane_b32 s4, v131
	s_cmp_lg_u32 s4, 0
	s_cbranch_scc1 .Lpf_have_l
	v_mov_b32_e32 v1, 1
	global_atomic_add v1, v129, v1, s[38:39] offset:4 sc0
	s_waitcnt vmcnt(0)
	s_branch .Lpf_map_l
.Lpf_have_l:
	s_waitcnt vmcnt(0)
	v_mov_b32_e32 v1, v130
	v_mov_b32_e32 v131, 0
.Lpf_map_l:
	ds_write_b32 v129, v1 offset:32

; #define MFMA16(a, b, c) __builtin_amdgcn_mfma_f32_16x16x32_bf16((a), (b), (c), 0, 0, 0)
; DI float sigm(float x) { return __builtin_amdgcn_rcpf(1.f + __expf(-x)); }
; DI void lru_tile(const Params& p, int layer, int isP, int sq, int tile, int nb, int pass, char*) {
;     ...
;   {
;     bf16x8 af0 = *(const bf16x8*)(xca + (wid * 16 + fr) * 72 + fq * 8);
;     bf16x8 af1 = *(const bf16x8*)(xca + (wid * 16 + fr) * 72 + 32 + fq * 8);
; #pragma unroll
;     for (int nt = 0; nt < 4; ++nt) {
;       const int d = nt * 16 + fr;
;       const bf16x8 ba0 = wfa0[nt], ba1 = wfa1[nt], bx0 = wfx0[nt], bx1 = wfx1[nt];
;       f32x4 ar = {0.f, 0.f, 0.f, 0.f}, ai = {0.f, 0.f, 0.f, 0.f};
;       ar = MFMA16(af0, ba0, ar); ar = MFMA16(af1, ba1, ar);
;       ai = MFMA16(af0, bx0, ai); ai = MFMA16(af1, bx1, ai);
;       const float bav = pbav[nt], bxv = pbxv[nt];
;       const float sp = log1pf(__expf(-plam[nt]));
; #pragma unroll
;       for (int j = 0; j < 4; ++j) {
;         const int t = wid * 16 + fq * 4 + j;
;         float r = sigm(ar[j] + bav), ig = sigm(ai[j] + bxv);
;         float la = -8.f * r * sp;
;         float a = __expf(la);
;         float b = sqrtf(1.f - __expf(2.f * la)) * (ig * xcs[t * 64 + d]);
;         if (t0 + t >= T) { a = 1.f; b = 0.f; }
;         as_[t * 64 + d] = a;
;         bs_[t * 64 + d] = b;
;       }
;     }
;   }
; DI int pop_block(int* ctr, int*) {
;   __syncthreads();
;   if (threadIdx.x == 0) sh_item = atomicAdd(ctr, 1);
;   __syncthreads();
;   return __builtin_amdgcn_readfirstlane(sh_item);
; }
.Llc_pdone:
	s_and_saveexec_b64 s[0:1], s[96:97]
	v_mov_b32_e32 v131, 1
	v_mov_b32_e32 v130, 1
	global_atomic_add v130, v129, v130, s[38:39] offset:4 sc0
	s_or_b64 exec, exec, s[0:1]
	v_mul_f32_e32 v76, 0xbfb8aa3b, v96
	s_waitcnt lgkmcnt(1)
	v_mfma_f32_16x16x32_bf16 v[56:59], v[68:71], v[56:59], 0
	v_exp_f32_e32 v76, v76
	s_mov_b32 s12, 0x3f2aaaab
	s_mov_b32 s13, 0x3f317218
	v_mfma_f32_16x16x32_bf16 v[60:63], v[68:71], v[60:63], 0
	s_mov_b32 s14, 0x7f800000
	s_mov_b32 s15, 0x33800000
	s_mov_b32 s16, 0xf800000
	s_waitcnt lgkmcnt(0)
	v_mfma_f32_16x16x32_bf16 v[56:59], v[64:67], v[48:51], v[56:59]
	s_mov_b32 s11, 0
	v_mfma_f32_16x16x32_bf16 v[48:51], v[64:67], v[52:55], v[60:63]
	v_add_f32_e32 v54, 1.0, v76
	v_add_f32_e32 v52, -1.0, v54
	v_sub_f32_e32 v53, v52, v54
	v_add_f32_e32 v53, 1.0, v53
	v_sub_f32_e32 v52, v76, v52
	v_add_f32_e32 v55, v52, v53
	v_frexp_mant_f32_e32 v60, v54
	v_cvt_f64_f32_e32 v[52:53], v54
	v_frexp_exp_i32_f64_e32 v52, v[52:53]
	v_cmp_gt_f32_e32 vcc, s12, v60
	v_add_f32_e32 v48, v93, v48
	v_mul_f32_e32 v48, 0xbfb8aa3b, v48
	v_subbrev_co_u32_e32 v52, vcc, 0, v52, vcc
	v_sub_u32_e32 v53, 0, v52
	v_ldexp_f32 v54, v54, v53
	v_ldexp_f32 v53, v55, v53
	v_add_f32_e32 v55, -1.0, v54
	v_add_f32_e32 v62, 1.0, v54
	v_add_f32_e32 v60, 1.0, v55
	v_add_f32_e32 v63, -1.0, v62
	v_sub_f32_e32 v60, v54, v60
	v_sub_f32_e32 v54, v54, v63
	v_add_f32_e32 v60, v53, v60
	v_add_f32_e32 v53, v53, v54
	v_add_f32_e32 v54, v62, v53
	v_rcp_f32_e32 v63, v54
	v_add_f32_e32 v61, v55, v60
	v_sub_f32_e32 v55, v61, v55
	v_sub_f32_e32 v55, v60, v55
	v_sub_f32_e32 v60, v54, v62
	v_sub_f32_e32 v53, v53, v60
	v_mul_f32_e32 v60, v61, v63
	v_mul_f32_e32 v62, v54, v60
	v_fma_f32 v77, v60, v54, -v62
	v_fmac_f32_e32 v77, v60, v53
	v_add_f32_e32 v78, v62, v77
	v_sub_f32_e32 v79, v61, v78
	v_sub_f32_e32 v61, v61, v79
	v_sub_f32_e32 v62, v78, v62
	v_sub_f32_e32 v61, v61, v78
	v_add_f32_e32 v55, v55, v61
	v_sub_f32_e32 v61, v62, v77
	v_add_f32_e32 v55, v61, v55
	v_add_f32_e32 v61, v79, v55
	v_mul_f32_e32 v62, v63, v61
	v_mul_f32_e32 v77, v54, v62
	v_fma_f32 v54, v62, v54, -v77
	v_fmac_f32_e32 v54, v62, v53
	v_sub_f32_e32 v53, v79, v61
	v_add_f32_e32 v53, v55, v53
	v_add_f32_e32 v55, v77, v54
	v_sub_f32_e32 v78, v61, v55
	v_sub_f32_e32 v61, v61, v78
	v_sub_f32_e32 v77, v55, v77
	v_sub_f32_e32 v55, v61, v55
	v_add_f32_e32 v53, v53, v55
	v_sub_f32_e32 v54, v77, v54
	v_cvt_f32_i32_e32 v52, v52
	v_add_f32_e32 v53, v54, v53
	v_add_f32_e32 v54, v60, v62
	v_add_f32_e32 v53, v78, v53
	v_sub_f32_e32 v55, v54, v60
	v_mul_f32_e32 v53, v63, v53
	v_sub_f32_e32 v55, v62, v55
	v_add_f32_e32 v53, v55, v53
	v_mul_f32_e32 v62, 0x3f317218, v52
	v_add_f32_e32 v55, v54, v53
	v_fma_f32 v63, v52, s13, -v62
	v_mul_f32_e32 v60, v55, v55
	v_fmac_f32_e32 v63, 0xb102e308, v52
	v_sub_f32_e32 v52, v55, v54
	v_fmamk_f32 v61, v60, 0x3e9b6dac, v160
	v_sub_f32_e32 v52, v53, v52
	v_add_f32_e32 v53, v62, v63
	v_fmaak_f32 v61, v60, v61, 0x3f2aaada
	v_sub_f32_e32 v54, v53, v62
	v_ldexp_f32 v62, v55, 1
	v_mul_f32_e32 v55, v55, v60
	v_mul_f32_e32 v55, v55, v61
	v_add_f32_e32 v60, v62, v55
	v_sub_f32_e32 v61, v60, v62
	v_ldexp_f32 v52, v52, 1
	v_sub_f32_e32 v55, v55, v61
	v_add_f32_e32 v52, v52, v55
	v_add_f32_e32 v55, v60, v52
	v_sub_f32_e32 v60, v55, v60
	v_sub_f32_e32 v52, v52, v60
	v_add_f32_e32 v60, v53, v55
	v_sub_f32_e32 v61, v60, v53
	v_sub_f32_e32 v62, v60, v61
	v_sub_f32_e32 v54, v63, v54
	v_sub_f32_e32 v53, v53, v62
	v_sub_f32_e32 v55, v55, v61
	v_add_f32_e32 v53, v55, v53
	v_add_f32_e32 v55, v54, v52
	v_sub_f32_e32 v61, v55, v54
	v_sub_f32_e32 v62, v55, v61
	v_sub_f32_e32 v54, v54, v62
	v_sub_f32_e32 v52, v52, v61
	v_add_f32_e32 v53, v55, v53
	v_add_f32_e32 v52, v52, v54
	v_add_f32_e32 v54, v60, v53
	v_sub_f32_e32 v55, v54, v60
	v_sub_f32_e32 v53, v53, v55
	v_add_f32_e32 v52, v52, v53
	v_add_f32_e32 v53, v92, v56
	v_mul_f32_e32 v53, 0xbfb8aa3b, v53
	v_exp_f32_e32 v53, v53
	v_add_f32_e32 v52, v54, v52
	v_cmp_neq_f32_e32 vcc, s14, v76
	v_exp_f32_e32 v48, v48
	v_add_f32_e32 v53, 1.0, v53
	v_rcp_f32_e32 v53, v53
	v_cndmask_b32_e32 v52, v177, v52, vcc
	v_cmp_ngt_f32_e32 vcc, -1.0, v76
	v_add_f32_e32 v48, 1.0, v48
	v_mul_f32_e32 v53, 0xc1000000, v53
	v_cndmask_b32_e32 v52, v178, v52, vcc
	v_cmp_neq_f32_e32 vcc, -1.0, v76
	v_rcp_f32_e32 v60, v48
	v_lshl_or_b32 v55, v73, 2, s10
	v_cndmask_b32_e32 v52, v179, v52, vcc
	v_cmp_lt_f32_e64 vcc, |v76|, s15
	v_add_f32_e32 v57, v92, v57
	v_mul_f32_e32 v57, 0xbfb8aa3b, v57
	v_cndmask_b32_e32 v52, v52, v76, vcc
	v_mul_f32_e32 v53, v52, v53
	v_add_f32_e32 v54, v53, v53
	v_mul_f32_e32 v54, 0x3fb8aa3b, v54
	v_exp_f32_e32 v54, v54
	v_mul_f32_e32 v48, 0x3fb8aa3b, v53
	v_exp_f32_e32 v53, v48
	v_exp_f32_e32 v57, v57
	v_sub_f32_e32 v54, 1.0, v54
	v_mul_f32_e32 v56, 0x4f800000, v54
	v_cmp_gt_f32_e32 vcc, s16, v54
	v_add_f32_e32 v49, v93, v49
	v_mul_f32_e32 v49, 0xbfb8aa3b, v49
	v_cndmask_b32_e32 v54, v54, v56, vcc
	v_sqrt_f32_e32 v56, v54
	v_exp_f32_e32 v49, v49
	v_add_f32_e32 v50, v93, v50
	v_mul_f32_e32 v50, 0xbfb8aa3b, v50
	v_add_u32_e32 v48, -1, v56
	v_fma_f32 v61, -v48, v56, v54
	v_cmp_ge_f32_e64 s[0:1], 0, v61
	v_add_u32_e32 v61, 1, v56
	v_add_f32_e32 v49, 1.0, v49
	v_cndmask_b32_e64 v48, v56, v48, s[0:1]
	v_fma_f32 v56, -v61, v56, v54
	v_cmp_lt_f32_e64 s[0:1], 0, v56
	v_exp_f32_e32 v50, v50
	v_add_f32_e32 v51, v93, v51
	v_cndmask_b32_e64 v56, v48, v61, s[0:1]
	v_lshlrev_b32_e32 v61, 2, v74
	v_lshl_or_b32 v48, v55, 8, v61
	v_add_u32_e32 v48, 0x80, v48
	ds_read_b32 v62, v48 offset:17152
	v_mul_f32_e32 v63, 0x37800000, v56
	v_cndmask_b32_e32 v56, v56, v63, vcc
	v_cmp_class_f32_e32 vcc, v54, v161
	v_add_f32_e32 v50, 1.0, v50
	v_mul_f32_e32 v51, 0xbfb8aa3b, v51
	v_cndmask_b32_e32 v54, v56, v54, vcc
	s_waitcnt lgkmcnt(0)
; #define MFMA16(a, b, c) __builtin_amdgcn_mfma_f32_16x16x32_bf16((a), (b), (c), 0, 0, 0)
; DI float sigm(float x) { return __builtin_amdgcn_rcpf(1.f + __expf(-x)); }
; DI void lru_tile(const Params& p, int layer, int isP, int sq, int tile, int nb, int pass, char*) {
;     ...
;     for (int nt = 0; nt < 4; ++nt) {
;       const int d = nt * 16 + fr;
;       const bf16x8 ba0 = wfa0[nt], ba1 = wfa1[nt], bx0 = wfx0[nt], bx1 = wfx1[nt];
;       f32x4 ar = {0.f, 0.f, 0.f, 0.f}, ai = {0.f, 0.f, 0.f, 0.f};
;       ar = MFMA16(af0, ba0, ar); ar = MFMA16(af1, ba1, ar);
;       ai = MFMA16(af0, bx0, ai); ai = MFMA16(af1, bx1, ai);
;       const float bav = pbav[nt], bxv = pbxv[nt];
;       const float sp = log1pf(__expf(-plam[nt]));
; #pragma unroll
;       for (int j = 0; j < 4; ++j) {
;         const int t = wid * 16 + fq * 4 + j;
;         float r = sigm(ar[j] + bav), ig = sigm(ai[j] + bxv);
;         float la = -8.f * r * sp;
;         float a = __expf(la);
;         float b = sqrtf(1.f - __expf(2.f * la)) * (ig * xcs[t * 64 + d]);
;         if (t0 + t >= T) { a = 1.f; b = 0.f; }
;         as_[t * 64 + d] = a;
;         bs_[t * 64 + d] = b;
;       }
;     }
	v_mul_f32_e32 v56, v62, v60
	v_mul_f32_e32 v54, v56, v54
	v_add_u32_e32 v56, s44, v55
	v_cmp_gt_i32_e32 vcc, s92, v56
	v_rcp_f32_e32 v60, v49
	v_exp_f32_e32 v51, v51
	v_cndmask_b32_e32 v53, 1.0, v53, vcc
	ds_write_b32 v48, v53
	v_add_f32_e32 v53, 1.0, v57
	v_rcp_f32_e32 v53, v53
	v_cndmask_b32_e32 v54, 0, v54, vcc
	ds_write_b32 v48, v54 offset:33536
	v_or_b32_e32 v54, 1, v55
	v_mul_f32_e32 v53, 0xc1000000, v53
	v_mul_f32_e32 v53, v52, v53
	v_add_f32_e32 v56, v53, v53
	v_mul_f32_e32 v56, 0x3fb8aa3b, v56
	v_exp_f32_e32 v56, v56
	v_mul_f32_e32 v49, 0x3fb8aa3b, v53
	v_exp_f32_e32 v53, v49
	v_mfma_f32_16x16x32_bf16 v[44:47], v[68:71], v[44:47], 0
	v_sub_f32_e32 v56, 1.0, v56
	v_mul_f32_e32 v57, 0x4f800000, v56
	v_cmp_gt_f32_e64 s[0:1], s16, v56
	v_add_f32_e32 v51, 1.0, v51
	v_mfma_f32_16x16x32_bf16 v[40:43], v[64:67], v[40:43], v[44:47]
	v_cndmask_b32_e64 v56, v56, v57, s[0:1]
	v_sqrt_f32_e32 v57, v56
	s_nop 0
	v_mul_f32_e32 v46, 0xbfb8aa3b, v94
	v_mfma_f32_16x16x32_bf16 v[36:39], v[68:71], v[36:39], 0
	v_add_u32_e32 v49, -1, v57
	v_fma_f32 v62, -v49, v57, v56
	v_cmp_ge_f32_e64 s[2:3], 0, v62
	v_add_u32_e32 v62, 1, v57
	v_exp_f32_e32 v46, v46
	v_cndmask_b32_e64 v49, v57, v49, s[2:3]
	v_fma_f32 v57, -v62, v57, v56
	v_cmp_lt_f32_e64 s[2:3], 0, v57
	v_mfma_f32_16x16x32_bf16 v[32:35], v[64:67], v[32:35], v[36:39]
	s_nop 0
	v_cndmask_b32_e64 v57, v49, v62, s[2:3]
	v_lshl_or_b32 v49, v54, 8, v61
	v_add_u32_e32 v49, 0x80, v49
	ds_read_b32 v62, v49 offset:17152
	v_mul_f32_e32 v63, 0x37800000, v57
	v_cndmask_b32_e64 v57, v57, v63, s[0:1]
	v_cmp_class_f32_e64 s[0:1], v56, v161
	v_add_u32_e32 v54, s44, v54
	v_add_f32_e32 v38, 1.0, v46
	v_cndmask_b32_e64 v56, v57, v56, s[0:1]
	s_waitcnt lgkmcnt(0)
	v_mul_f32_e32 v57, v62, v60
	v_mul_f32_e32 v56, v57, v56
	v_add_f32_e32 v57, v92, v58
	v_mul_f32_e32 v57, 0xbfb8aa3b, v57
	v_exp_f32_e32 v57, v57
	v_cmp_gt_i32_e64 s[0:1], s92, v54
	v_rcp_f32_e32 v58, v50
	v_add_f32_e32 v36, -1.0, v38
	v_cndmask_b32_e64 v53, 1.0, v53, s[0:1]
	ds_write_b32 v49, v53
	v_add_f32_e32 v53, 1.0, v57
	v_rcp_f32_e32 v53, v53
	v_cndmask_b32_e64 v54, 0, v56, s[0:1]
	ds_write_b32 v49, v54 offset:33536
	v_or_b32_e32 v54, 2, v55
	v_mul_f32_e32 v53, 0xc1000000, v53
	v_mul_f32_e32 v53, v52, v53
	v_add_f32_e32 v56, v53, v53
	v_mul_f32_e32 v56, 0x3fb8aa3b, v56
	v_exp_f32_e32 v56, v56
	v_mul_f32_e32 v50, 0x3fb8aa3b, v53
	v_exp_f32_e32 v53, v50
	v_sub_f32_e32 v37, v36, v38
	v_sub_f32_e32 v56, 1.0, v56
	v_mul_f32_e32 v57, 0x4f800000, v56
	v_cmp_gt_f32_e64 s[2:3], s16, v56
	v_add_f32_e32 v37, 1.0, v37
	v_sub_f32_e32 v36, v46, v36
	v_cndmask_b32_e64 v56, v56, v57, s[2:3]
	v_sqrt_f32_e32 v57, v56
	v_add_f32_e32 v39, v36, v37
	v_frexp_mant_f32_e32 v47, v38
	v_cvt_f64_f32_e32 v[36:37], v38
	v_add_u32_e32 v50, -1, v57
	v_fma_f32 v60, -v50, v57, v56
	v_cmp_ge_f32_e64 s[4:5], 0, v60
	v_add_u32_e32 v60, 1, v57
	v_frexp_exp_i32_f64_e32 v36, v[36:37]
	v_cndmask_b32_e64 v50, v57, v50, s[4:5]
	v_fma_f32 v57, -v60, v57, v56
	v_cmp_lt_f32_e64 s[4:5], 0, v57
	v_add_f32_e32 v32, v90, v32
	v_mul_f32_e32 v32, 0xbfb8aa3b, v32
	v_cndmask_b32_e64 v57, v50, v60, s[4:5]
	v_lshl_or_b32 v50, v54, 8, v61
	v_add_u32_e32 v50, 0x80, v50
	ds_read_b32 v60, v50 offset:17152
	v_mul_f32_e32 v62, 0x37800000, v57
	v_cndmask_b32_e64 v57, v57, v62, s[2:3]
	v_cmp_class_f32_e64 s[2:3], v56, v161
	v_add_u32_e32 v54, s44, v54
	v_exp_f32_e32 v32, v32
	v_cndmask_b32_e64 v56, v57, v56, s[2:3]
	s_waitcnt lgkmcnt(0)
	v_mul_f32_e32 v57, v58, v60
	v_mul_f32_e32 v56, v57, v56
	v_add_f32_e32 v57, v92, v59
	v_mul_f32_e32 v57, 0xbfb8aa3b, v57
	v_exp_f32_e32 v57, v57
	v_cmp_gt_i32_e64 s[2:3], s92, v54
	v_add_f32_e32 v32, 1.0, v32
	v_rcp_f32_e32 v32, v32
	v_cndmask_b32_e64 v53, 1.0, v53, s[2:3]
	ds_write_b32 v50, v53
	v_add_f32_e32 v53, 1.0, v57
	v_rcp_f32_e32 v53, v53
	v_cndmask_b32_e64 v54, 0, v56, s[2:3]
	ds_write_b32 v50, v54 offset:33536
	v_or_b32_e32 v54, 3, v55
	v_mul_f32_e32 v53, 0xc1000000, v53
	v_mul_f32_e32 v52, v52, v53
	v_add_f32_e32 v53, v52, v52
	v_mul_f32_e32 v53, 0x3fb8aa3b, v53
	v_exp_f32_e32 v53, v53
	v_rcp_f32_e32 v56, v51
	v_mul_f32_e32 v51, 0x3fb8aa3b, v52
	v_exp_f32_e32 v52, v51
	v_sub_f32_e32 v53, 1.0, v53
	v_mul_f32_e32 v55, 0x4f800000, v53
	v_cmp_gt_f32_e64 s[4:5], s16, v53
	v_add_u32_e32 v45, s44, v54
	v_add_f32_e32 v33, v90, v33
	v_cndmask_b32_e64 v53, v53, v55, s[4:5]
	v_sqrt_f32_e32 v55, v53
	v_mul_f32_e32 v33, 0xbfb8aa3b, v33
	v_exp_f32_e32 v33, v33
	v_add_f32_e32 v34, v90, v34
	v_add_u32_e32 v51, -1, v55
	v_fma_f32 v57, -v51, v55, v53
	v_cmp_ge_f32_e64 s[6:7], 0, v57
	v_add_u32_e32 v57, 1, v55
	v_mul_f32_e32 v34, 0xbfb8aa3b, v34
	v_cndmask_b32_e64 v51, v55, v51, s[6:7]
	v_fma_f32 v55, -v57, v55, v53
	v_cmp_lt_f32_e64 s[6:7], 0, v55
	v_exp_f32_e32 v34, v34
	v_add_f32_e32 v35, v90, v35
	v_cndmask_b32_e64 v55, v51, v57, s[6:7]
	v_lshl_or_b32 v51, v54, 8, v61
	v_add_u32_e32 v51, 0x80, v51
	ds_read_b32 v58, v51 offset:17152
	v_cmp_gt_f32_e64 s[6:7], s12, v47
	v_mul_f32_e32 v57, 0x37800000, v55
	v_cndmask_b32_e64 v55, v55, v57, s[4:5]
	v_subbrev_co_u32_e64 v36, s[6:7], 0, v36, s[6:7]
	v_cmp_class_f32_e64 s[4:5], v53, v161
	v_sub_u32_e32 v37, 0, v36
	s_waitcnt lgkmcnt(0)
; #define MFMA16(a, b, c) __builtin_amdgcn_mfma_f32_16x16x32_bf16((a), (b), (c), 0, 0, 0)
; DI float sigm(float x) { return __builtin_amdgcn_rcpf(1.f + __expf(-x)); }
; DI void lru_tile(const Params& p, int layer, int isP, int sq, int tile, int nb, int pass, char*) {
;     ...
;     for (int nt = 0; nt < 4; ++nt) {
;       const int d = nt * 16 + fr;
;       const bf16x8 ba0 = wfa0[nt], ba1 = wfa1[nt], bx0 = wfx0[nt], bx1 = wfx1[nt];
;       f32x4 ar = {0.f, 0.f, 0.f, 0.f}, ai = {0.f, 0.f, 0.f, 0.f};
;       ar = MFMA16(af0, ba0, ar); ar = MFMA16(af1, ba1, ar);
;       ai = MFMA16(af0, bx0, ai); ai = MFMA16(af1, bx1, ai);
;       const float bav = pbav[nt], bxv = pbxv[nt];
;       const float sp = log1pf(__expf(-plam[nt]));
; #pragma unroll
;       for (int j = 0; j < 4; ++j) {
;         const int t = wid * 16 + fq * 4 + j;
;         float r = sigm(ar[j] + bav), ig = sigm(ai[j] + bxv);
;         float la = -8.f * r * sp;
;         float a = __expf(la);
;         float b = sqrtf(1.f - __expf(2.f * la)) * (ig * xcs[t * 64 + d]);
;         if (t0 + t >= T) { a = 1.f; b = 0.f; }
;         as_[t * 64 + d] = a;
;         bs_[t * 64 + d] = b;
;       }
;     }
	v_mul_f32_e32 v44, v56, v58
	v_cndmask_b32_e64 v53, v55, v53, s[4:5]
	v_ldexp_f32 v38, v38, v37
	v_mul_f32_e32 v44, v53, v44
	v_ldexp_f32 v37, v39, v37
	v_add_f32_e32 v39, -1.0, v38
	v_add_f32_e32 v53, 1.0, v38
	v_add_f32_e32 v47, 1.0, v39
	v_add_f32_e32 v54, -1.0, v53
	v_sub_f32_e32 v47, v38, v47
	v_sub_f32_e32 v38, v38, v54
	v_add_f32_e32 v47, v37, v47
	v_add_f32_e32 v37, v37, v38
	v_add_f32_e32 v38, v53, v37
	v_cmp_gt_i32_e64 s[4:5], s92, v45
	v_rcp_f32_e32 v54, v38
	v_cvt_f32_i32_e32 v36, v36
	v_cndmask_b32_e64 v45, 1.0, v52, s[4:5]
	v_add_f32_e32 v52, v39, v47
	v_sub_f32_e32 v39, v52, v39
	v_sub_f32_e32 v39, v47, v39
	v_sub_f32_e32 v47, v38, v53
	v_sub_f32_e32 v37, v37, v47
	v_mul_f32_e32 v47, v52, v54
	v_mul_f32_e32 v53, v38, v47
	v_fma_f32 v55, v47, v38, -v53
	v_fmac_f32_e32 v55, v47, v37
	v_add_f32_e32 v56, v53, v55
	v_sub_f32_e32 v57, v52, v56
	v_sub_f32_e32 v52, v52, v57
	v_sub_f32_e32 v53, v56, v53
	v_sub_f32_e32 v52, v52, v56
	v_add_f32_e32 v39, v39, v52
	v_sub_f32_e32 v52, v53, v55
	v_add_f32_e32 v39, v52, v39
	v_add_f32_e32 v52, v57, v39
	v_mul_f32_e32 v53, v54, v52
	v_mul_f32_e32 v55, v38, v53
	v_fma_f32 v38, v53, v38, -v55
	v_fmac_f32_e32 v38, v53, v37
	v_sub_f32_e32 v37, v57, v52
	v_add_f32_e32 v37, v39, v37
	v_add_f32_e32 v39, v55, v38
	v_sub_f32_e32 v56, v52, v39
	v_sub_f32_e32 v52, v52, v56
	v_sub_f32_e32 v55, v39, v55
	v_sub_f32_e32 v39, v52, v39
	v_add_f32_e32 v37, v37, v39
	v_sub_f32_e32 v38, v55, v38
	v_add_f32_e32 v37, v38, v37
	v_add_f32_e32 v38, v47, v53
	v_add_f32_e32 v37, v56, v37
	v_sub_f32_e32 v39, v38, v47
	v_mul_f32_e32 v37, v54, v37
	v_sub_f32_e32 v39, v53, v39
	v_add_f32_e32 v37, v39, v37
	v_mul_f32_e32 v53, 0x3f317218, v36
	v_add_f32_e32 v39, v38, v37
	v_fma_f32 v54, v36, s13, -v53
	v_mul_f32_e32 v47, v39, v39
	v_fmac_f32_e32 v54, 0xb102e308, v36
	v_sub_f32_e32 v36, v39, v38
	v_fmamk_f32 v52, v47, 0x3e9b6dac, v160
	v_sub_f32_e32 v36, v37, v36
	v_add_f32_e32 v37, v53, v54
	v_fmaak_f32 v52, v47, v52, 0x3f2aaada
	v_sub_f32_e32 v38, v37, v53
	v_ldexp_f32 v53, v39, 1
	v_mul_f32_e32 v39, v39, v47
	v_mul_f32_e32 v39, v39, v52
	v_add_f32_e32 v47, v53, v39
	v_sub_f32_e32 v52, v47, v53
	v_ldexp_f32 v36, v36, 1
	v_sub_f32_e32 v39, v39, v52
	v_add_f32_e32 v36, v36, v39
	v_add_f32_e32 v39, v47, v36
	v_sub_f32_e32 v47, v39, v47
	v_sub_f32_e32 v36, v36, v47
	v_add_f32_e32 v47, v37, v39
	v_sub_f32_e32 v52, v47, v37
	v_sub_f32_e32 v53, v47, v52
	v_sub_f32_e32 v38, v54, v38
	v_sub_f32_e32 v37, v37, v53
	v_sub_f32_e32 v39, v39, v52
	v_add_f32_e32 v37, v39, v37
	v_add_f32_e32 v39, v38, v36
	v_sub_f32_e32 v52, v39, v38
	v_sub_f32_e32 v53, v39, v52
	v_sub_f32_e32 v38, v38, v53
	v_sub_f32_e32 v36, v36, v52
	v_add_f32_e32 v37, v39, v37
	v_add_f32_e32 v36, v36, v38
	v_add_f32_e32 v38, v47, v37
	v_sub_f32_e32 v39, v38, v47
	v_sub_f32_e32 v37, v37, v39
	v_add_f32_e32 v36, v36, v37
	v_add_f32_e32 v37, v91, v40
	v_mul_f32_e32 v37, 0xbfb8aa3b, v37
	v_exp_f32_e32 v37, v37
	v_add_f32_e32 v36, v38, v36
	v_cmp_neq_f32_e64 s[6:7], s14, v46
	v_cndmask_b32_e64 v44, 0, v44, s[4:5]
	v_add_f32_e32 v37, 1.0, v37
	v_rcp_f32_e32 v37, v37
	v_cndmask_b32_e64 v36, v177, v36, s[6:7]
	v_cmp_ngt_f32_e64 s[6:7], -1.0, v46
	ds_write_b32 v51, v45
	ds_write_b32 v51, v44 offset:33536
	v_cndmask_b32_e64 v36, v178, v36, s[6:7]
	v_cmp_neq_f32_e64 s[6:7], -1.0, v46
	v_mul_f32_e32 v37, 0xc1000000, v37
	v_mul_f32_e32 v35, 0xbfb8aa3b, v35
	v_cndmask_b32_e64 v36, v179, v36, s[6:7]
	v_cmp_lt_f32_e64 s[6:7], |v46|, s15
	v_exp_f32_e32 v35, v35
	v_mfma_f32_16x16x32_bf16 v[28:31], v[68:71], v[28:31], 0
	v_cndmask_b32_e64 v36, v36, v46, s[6:7]
	v_mul_f32_e32 v37, v36, v37
	v_add_f32_e32 v38, v37, v37
	v_mul_f32_e32 v38, 0x3fb8aa3b, v38
	v_exp_f32_e32 v38, v38
	v_mul_f32_e32 v37, 0x3fb8aa3b, v37
	v_exp_f32_e32 v37, v37
	v_mfma_f32_16x16x32_bf16 v[24:27], v[64:67], v[24:27], v[28:31]
	v_sub_f32_e32 v38, 1.0, v38
	v_mul_f32_e32 v39, 0x4f800000, v38
	v_cmp_gt_f32_e64 s[6:7], s16, v38
	v_cndmask_b32_e32 v37, 1.0, v37, vcc
	v_mfma_f32_16x16x32_bf16 v[20:23], v[68:71], v[20:23], 0
	v_cndmask_b32_e64 v38, v38, v39, s[6:7]
	v_sqrt_f32_e32 v39, v38
	v_mfma_f32_16x16x32_bf16 v[16:19], v[64:67], v[16:19], v[20:23]
	v_add_u32_e32 v40, -1, v39
	v_fma_f32 v44, -v40, v39, v38
	v_cmp_ge_f32_e64 s[8:9], 0, v44
	v_add_u32_e32 v44, 1, v39
	s_nop 3
	v_add_f32_e32 v16, v87, v16
	v_cndmask_b32_e64 v40, v39, v40, s[8:9]
	v_fma_f32 v39, -v44, v39, v38
	v_cmp_lt_f32_e64 s[8:9], 0, v39
	v_mul_f32_e32 v16, 0xbfb8aa3b, v16
	v_exp_f32_e32 v16, v16
	v_cndmask_b32_e64 v39, v40, v44, s[8:9]
	v_mul_f32_e32 v44, 0x37800000, v39
	v_cndmask_b32_e64 v39, v39, v44, s[6:7]
	v_cmp_class_f32_e64 s[6:7], v38, v161
	ds_read_b32 v40, v48 offset:17216
	v_add_f32_e32 v16, 1.0, v16
	v_cndmask_b32_e64 v38, v39, v38, s[6:7]
	v_add_f32_e32 v39, v91, v41
	v_mul_f32_e32 v39, 0xbfb8aa3b, v39
	v_exp_f32_e32 v39, v39
	s_waitcnt lgkmcnt(0)
	v_mul_f32_e32 v32, v40, v32
	v_mul_f32_e32 v32, v32, v38
	v_cndmask_b32_e32 v32, 0, v32, vcc
	v_add_f32_e32 v38, 1.0, v39
	v_rcp_f32_e32 v38, v38
	ds_write_b32 v48, v37 offset:64
	ds_write_b32 v48, v32 offset:33600
	v_add_f32_e32 v32, 1.0, v33
	v_rcp_f32_e32 v32, v32
	v_mul_f32_e32 v38, 0xc1000000, v38
	v_mul_f32_e32 v38, v36, v38
	v_add_f32_e32 v39, v38, v38
	v_mul_f32_e32 v39, 0x3fb8aa3b, v39
	v_exp_f32_e32 v39, v39
	v_mul_f32_e32 v38, 0x3fb8aa3b, v38
	v_exp_f32_e32 v38, v38
	v_rcp_f32_e32 v16, v16
	v_sub_f32_e32 v33, 1.0, v39
	v_mul_f32_e32 v37, 0x4f800000, v33
	v_cmp_gt_f32_e64 s[6:7], s16, v33
	v_add_f32_e32 v17, v87, v17
	v_mul_f32_e32 v17, 0xbfb8aa3b, v17
	v_cndmask_b32_e64 v33, v33, v37, s[6:7]
	v_sqrt_f32_e32 v37, v33
	v_exp_f32_e32 v17, v17
	v_add_f32_e32 v18, v87, v18
	v_mul_f32_e32 v18, 0xbfb8aa3b, v18
	v_add_u32_e32 v39, -1, v37
	v_fma_f32 v40, -v39, v37, v33
	v_cmp_ge_f32_e64 s[8:9], 0, v40
	v_add_u32_e32 v40, 1, v37
	v_exp_f32_e32 v18, v18
	v_cndmask_b32_e64 v39, v37, v39, s[8:9]
	v_fma_f32 v37, -v40, v37, v33
	v_cmp_lt_f32_e64 s[8:9], 0, v37
	v_add_f32_e32 v19, v87, v19
	v_mul_f32_e32 v19, 0xbfb8aa3b, v19
	v_cndmask_b32_e64 v37, v39, v40, s[8:9]
	v_mul_f32_e32 v40, 0x37800000, v37
	v_cndmask_b32_e64 v37, v37, v40, s[6:7]
	v_cmp_class_f32_e64 s[6:7], v33, v161
	ds_read_b32 v39, v49 offset:17216
	v_exp_f32_e32 v19, v19
	v_cndmask_b32_e64 v33, v37, v33, s[6:7]
	v_add_f32_e32 v37, v91, v42
	v_mul_f32_e32 v37, 0xbfb8aa3b, v37
	v_exp_f32_e32 v37, v37
	s_waitcnt lgkmcnt(0)
; #define MFMA16(a, b, c) __builtin_amdgcn_mfma_f32_16x16x32_bf16((a), (b), (c), 0, 0, 0)
; DI float sigm(float x) { return __builtin_amdgcn_rcpf(1.f + __expf(-x)); }
; DI void lru_tile(const Params& p, int layer, int isP, int sq, int tile, int nb, int pass, char*) {
;     ...
; #pragma unroll
;     for (int nt = 0; nt < 4; ++nt) {
;       const int d = nt * 16 + fr;
;       const bf16x8 ba0 = wfa0[nt], ba1 = wfa1[nt], bx0 = wfx0[nt], bx1 = wfx1[nt];
;       f32x4 ar = {0.f, 0.f, 0.f, 0.f}, ai = {0.f, 0.f, 0.f, 0.f};
;       ar = MFMA16(af0, ba0, ar); ar = MFMA16(af1, ba1, ar);
;       ai = MFMA16(af0, bx0, ai); ai = MFMA16(af1, bx1, ai);
;       const float bav = pbav[nt], bxv = pbxv[nt];
;       const float sp = log1pf(__expf(-plam[nt]));
; #pragma unroll
;       for (int j = 0; j < 4; ++j) {
;         const int t = wid * 16 + fq * 4 + j;
;         float r = sigm(ar[j] + bav), ig = sigm(ai[j] + bxv);
;         float la = -8.f * r * sp;
;         float a = __expf(la);
;         float b = sqrtf(1.f - __expf(2.f * la)) * (ig * xcs[t * 64 + d]);
;         if (t0 + t >= T) { a = 1.f; b = 0.f; }
;         as_[t * 64 + d] = a;
;         bs_[t * 64 + d] = b;
;       }
;     }
	v_mul_f32_e32 v32, v39, v32
	v_mul_f32_e32 v32, v32, v33
	v_cndmask_b32_e64 v33, 1.0, v38, s[0:1]
	v_add_f32_e32 v37, 1.0, v37
	v_rcp_f32_e32 v37, v37
	v_cndmask_b32_e64 v32, 0, v32, s[0:1]
	ds_write_b32 v49, v33 offset:64
	ds_write_b32 v49, v32 offset:33600
	v_add_f32_e32 v32, 1.0, v34
	v_mul_f32_e32 v37, 0xc1000000, v37
	v_mul_f32_e32 v37, v36, v37
	v_add_f32_e32 v38, v37, v37
	v_mul_f32_e32 v38, 0x3fb8aa3b, v38
	v_exp_f32_e32 v38, v38
	v_rcp_f32_e32 v32, v32
	v_mul_f32_e32 v37, 0x3fb8aa3b, v37
	v_exp_f32_e32 v37, v37
	v_sub_f32_e32 v33, 1.0, v38
	v_mul_f32_e32 v34, 0x4f800000, v33
	v_cmp_gt_f32_e64 s[6:7], s16, v33
	v_mfma_f32_16x16x32_bf16 v[12:15], v[68:71], v[12:15], 0
	s_nop 0
	v_cndmask_b32_e64 v33, v33, v34, s[6:7]
	v_sqrt_f32_e32 v34, v33
	v_mfma_f32_16x16x32_bf16 v[8:11], v[64:67], v[8:11], v[12:15]
	v_add_u32_e32 v38, -1, v34
	v_fma_f32 v39, -v38, v34, v33
	v_cmp_ge_f32_e64 s[8:9], 0, v39
	v_add_u32_e32 v39, 1, v34
	v_mfma_f32_16x16x32_bf16 v[4:7], v[68:71], v[4:7], 0
	v_cndmask_b32_e64 v38, v34, v38, s[8:9]
	v_fma_f32 v34, -v39, v34, v33
	v_cmp_lt_f32_e64 s[8:9], 0, v34
	v_mfma_f32_16x16x32_bf16 v[0:3], v[64:67], v[0:3], v[4:7]
	s_nop 0
	v_cndmask_b32_e64 v34, v38, v39, s[8:9]
	v_mul_f32_e32 v39, 0x37800000, v34
	v_cndmask_b32_e64 v34, v34, v39, s[6:7]
	v_cmp_class_f32_e64 s[6:7], v33, v161
	ds_read_b32 v38, v50 offset:17216
	s_nop 1
	v_add_f32_e32 v0, v84, v0
	v_cndmask_b32_e64 v33, v34, v33, s[6:7]
	v_add_f32_e32 v34, v91, v43
	v_mul_f32_e32 v34, 0xbfb8aa3b, v34
	v_exp_f32_e32 v34, v34
	s_waitcnt lgkmcnt(0)
	v_mul_f32_e32 v32, v32, v38
	v_mul_f32_e32 v32, v32, v33
	v_cndmask_b32_e64 v33, 1.0, v37, s[2:3]
	v_add_f32_e32 v34, 1.0, v34
	v_rcp_f32_e32 v34, v34
	v_cndmask_b32_e64 v32, 0, v32, s[2:3]
	ds_write_b32 v50, v33 offset:64
	ds_write_b32 v50, v32 offset:33600
	v_add_f32_e32 v32, 1.0, v35
	v_mul_f32_e32 v34, 0xc1000000, v34
	v_mul_f32_e32 v34, v36, v34
	v_add_f32_e32 v36, v34, v34
	v_mul_f32_e32 v36, 0x3fb8aa3b, v36
	v_exp_f32_e32 v36, v36
	v_rcp_f32_e32 v32, v32
	v_mul_f32_e32 v34, 0x3fb8aa3b, v34
	v_exp_f32_e32 v34, v34
	v_sub_f32_e32 v33, 1.0, v36
	v_mul_f32_e32 v35, 0x4f800000, v33
	v_cmp_gt_f32_e64 s[6:7], s16, v33
	v_cndmask_b32_e64 v30, 1.0, v34, s[4:5]
	v_mul_f32_e32 v0, 0xbfb8aa3b, v0
	v_cndmask_b32_e64 v33, v33, v35, s[6:7]
	v_sqrt_f32_e32 v35, v33
	v_exp_f32_e32 v0, v0
	v_add_f32_e32 v1, v84, v1
	v_mul_f32_e32 v1, 0xbfb8aa3b, v1
	v_add_u32_e32 v36, -1, v35
	v_fma_f32 v37, -v36, v35, v33
	v_cmp_ge_f32_e64 s[8:9], 0, v37
	v_add_u32_e32 v37, 1, v35
	v_add_f32_e32 v0, 1.0, v0
	v_cndmask_b32_e64 v36, v35, v36, s[8:9]
	v_fma_f32 v35, -v37, v35, v33
	v_cmp_lt_f32_e64 s[8:9], 0, v35
	v_rcp_f32_e32 v0, v0
	v_exp_f32_e32 v1, v1
	v_cndmask_b32_e64 v35, v36, v37, s[8:9]
	ds_read_b32 v37, v51 offset:17216
	v_mul_f32_e32 v36, 0x37800000, v35
	v_cndmask_b32_e64 v35, v35, v36, s[6:7]
	v_cmp_class_f32_e64 s[6:7], v33, v161
	v_add_f32_e32 v2, v84, v2
	s_waitcnt lgkmcnt(0)
	v_mul_f32_e32 v29, v32, v37
	v_cndmask_b32_e64 v28, v35, v33, s[6:7]
	v_mul_f32_e32 v28, v28, v29
	v_mul_f32_e32 v29, 0xbfb8aa3b, v89
	v_exp_f32_e32 v29, v29
	v_cndmask_b32_e64 v28, 0, v28, s[4:5]
	ds_write_b32 v51, v30 offset:64
	ds_write_b32 v51, v28 offset:33600
	v_mul_f32_e32 v2, 0xbfb8aa3b, v2
	v_add_f32_e32 v22, 1.0, v29
	v_add_f32_e32 v20, -1.0, v22
	v_sub_f32_e32 v21, v20, v22
	v_add_f32_e32 v21, 1.0, v21
	v_sub_f32_e32 v20, v29, v20
	v_add_f32_e32 v23, v20, v21
	v_frexp_mant_f32_e32 v31, v22
	v_cvt_f64_f32_e32 v[20:21], v22
	v_frexp_exp_i32_f64_e32 v20, v[20:21]
	v_cmp_gt_f32_e64 s[6:7], s12, v31
	v_exp_f32_e32 v2, v2
	v_add_f32_e32 v3, v84, v3
	v_subbrev_co_u32_e64 v20, s[6:7], 0, v20, s[6:7]
	v_sub_u32_e32 v21, 0, v20
	v_ldexp_f32 v22, v22, v21
	v_ldexp_f32 v21, v23, v21
	v_add_f32_e32 v23, -1.0, v22
	v_add_f32_e32 v33, 1.0, v22
	v_add_f32_e32 v31, 1.0, v23
	v_add_f32_e32 v34, -1.0, v33
	v_sub_f32_e32 v31, v22, v31
	v_sub_f32_e32 v22, v22, v34
	v_add_f32_e32 v31, v21, v31
	v_add_f32_e32 v21, v21, v22
	v_add_f32_e32 v22, v33, v21
	v_rcp_f32_e32 v34, v22
	v_add_f32_e32 v32, v23, v31
	v_sub_f32_e32 v23, v32, v23
	v_sub_f32_e32 v23, v31, v23
	v_sub_f32_e32 v31, v22, v33
	v_sub_f32_e32 v21, v21, v31
	v_mul_f32_e32 v31, v32, v34
	v_mul_f32_e32 v33, v22, v31
	v_fma_f32 v35, v31, v22, -v33
	v_fmac_f32_e32 v35, v31, v21
	v_add_f32_e32 v36, v33, v35
	v_sub_f32_e32 v37, v32, v36
	v_sub_f32_e32 v32, v32, v37
	v_sub_f32_e32 v33, v36, v33
	v_sub_f32_e32 v32, v32, v36
	v_add_f32_e32 v23, v23, v32
	v_sub_f32_e32 v32, v33, v35
	v_add_f32_e32 v23, v32, v23
	v_add_f32_e32 v32, v37, v23
	v_mul_f32_e32 v33, v34, v32
	v_mul_f32_e32 v35, v22, v33
	v_fma_f32 v22, v33, v22, -v35
	v_fmac_f32_e32 v22, v33, v21
	v_sub_f32_e32 v21, v37, v32
	v_add_f32_e32 v21, v23, v21
	v_add_f32_e32 v23, v35, v22
	v_sub_f32_e32 v36, v32, v23
	v_sub_f32_e32 v32, v32, v36
	v_sub_f32_e32 v35, v23, v35
	v_sub_f32_e32 v23, v32, v23
	v_add_f32_e32 v21, v21, v23
	v_sub_f32_e32 v22, v35, v22
	v_cvt_f32_i32_e32 v20, v20
	v_add_f32_e32 v21, v22, v21
	v_add_f32_e32 v22, v31, v33
	v_add_f32_e32 v21, v36, v21
	v_sub_f32_e32 v23, v22, v31
	v_mul_f32_e32 v21, v34, v21
	v_sub_f32_e32 v23, v33, v23
	v_add_f32_e32 v21, v23, v21
	v_mul_f32_e32 v33, 0x3f317218, v20
	v_add_f32_e32 v23, v22, v21
	v_fma_f32 v34, v20, s13, -v33
	v_mul_f32_e32 v31, v23, v23
	v_fmac_f32_e32 v34, 0xb102e308, v20
	v_sub_f32_e32 v20, v23, v22
	v_fmamk_f32 v32, v31, 0x3e9b6dac, v160
	v_sub_f32_e32 v20, v21, v20
	v_add_f32_e32 v21, v33, v34
	v_fmaak_f32 v32, v31, v32, 0x3f2aaada
	v_sub_f32_e32 v22, v21, v33
	v_ldexp_f32 v33, v23, 1
	v_mul_f32_e32 v23, v23, v31
	v_mul_f32_e32 v23, v23, v32
	v_add_f32_e32 v31, v33, v23
	v_sub_f32_e32 v32, v31, v33
; DI float sigm(float x) { return __builtin_amdgcn_rcpf(1.f + __expf(-x)); }
; DI void lru_tile(const Params& p, int layer, int isP, int sq, int tile, int nb, int pass, char*) {
;     ...
;       const float bav = pbav[nt], bxv = pbxv[nt];
;       const float sp = log1pf(__expf(-plam[nt]));
; #pragma unroll
;       for (int j = 0; j < 4; ++j) {
;         const int t = wid * 16 + fq * 4 + j;
;         float r = sigm(ar[j] + bav), ig = sigm(ai[j] + bxv);
;         float la = -8.f * r * sp;
;         float a = __expf(la);
;         float b = sqrtf(1.f - __expf(2.f * la)) * (ig * xcs[t * 64 + d]);
;         if (t0 + t >= T) { a = 1.f; b = 0.f; }
;         as_[t * 64 + d] = a;
;         bs_[t * 64 + d] = b;
;       }
;     }
	v_ldexp_f32 v20, v20, 1
	v_sub_f32_e32 v23, v23, v32
	v_add_f32_e32 v20, v20, v23
	v_add_f32_e32 v23, v31, v20
	v_sub_f32_e32 v31, v23, v31
	v_sub_f32_e32 v20, v20, v31
	v_add_f32_e32 v31, v21, v23
	v_sub_f32_e32 v32, v31, v21
	v_sub_f32_e32 v33, v31, v32
	v_sub_f32_e32 v22, v34, v22
	v_sub_f32_e32 v21, v21, v33
	v_sub_f32_e32 v23, v23, v32
	v_add_f32_e32 v21, v23, v21
	v_add_f32_e32 v23, v22, v20
	v_sub_f32_e32 v32, v23, v22
	v_sub_f32_e32 v33, v23, v32
	v_sub_f32_e32 v22, v22, v33
	v_sub_f32_e32 v20, v20, v32
	v_add_f32_e32 v21, v23, v21
	v_add_f32_e32 v20, v20, v22
	v_add_f32_e32 v22, v31, v21
	v_sub_f32_e32 v23, v22, v31
	v_sub_f32_e32 v21, v21, v23
	v_add_f32_e32 v20, v20, v21
	v_add_f32_e32 v21, v88, v24
	v_mul_f32_e32 v21, 0xbfb8aa3b, v21
	v_exp_f32_e32 v21, v21
	v_add_f32_e32 v20, v22, v20
	v_cmp_neq_f32_e64 s[6:7], s14, v29
	v_mul_f32_e32 v3, 0xbfb8aa3b, v3
	v_add_f32_e32 v21, 1.0, v21
	v_rcp_f32_e32 v21, v21
	v_cndmask_b32_e64 v20, v177, v20, s[6:7]
	v_cmp_ngt_f32_e64 s[6:7], -1.0, v29
	v_exp_f32_e32 v3, v3
	v_mul_f32_e32 v21, 0xc1000000, v21
	v_cndmask_b32_e64 v20, v178, v20, s[6:7]
	v_cmp_neq_f32_e64 s[6:7], -1.0, v29
	s_nop 1
	v_cndmask_b32_e64 v20, v179, v20, s[6:7]
	v_cmp_lt_f32_e64 s[6:7], |v29|, s15
	s_nop 1
	v_cndmask_b32_e64 v20, v20, v29, s[6:7]
	v_mul_f32_e32 v21, v20, v21
	v_add_f32_e32 v22, v21, v21
	v_mul_f32_e32 v22, 0x3fb8aa3b, v22
	v_exp_f32_e32 v22, v22
	v_mul_f32_e32 v21, 0x3fb8aa3b, v21
	v_exp_f32_e32 v21, v21
	v_sub_f32_e32 v22, 1.0, v22
	v_mul_f32_e32 v23, 0x4f800000, v22
	v_cmp_gt_f32_e64 s[6:7], s16, v22
	v_cndmask_b32_e32 v21, 1.0, v21, vcc
	s_nop 0
	v_cndmask_b32_e64 v22, v22, v23, s[6:7]
	v_sqrt_f32_e32 v23, v22
	s_nop 0
	v_add_u32_e32 v24, -1, v23
	v_fma_f32 v28, -v24, v23, v22
	v_cmp_ge_f32_e64 s[8:9], 0, v28
	v_add_u32_e32 v28, 1, v23
	s_nop 0
	v_cndmask_b32_e64 v24, v23, v24, s[8:9]
	v_fma_f32 v23, -v28, v23, v22
	v_cmp_lt_f32_e64 s[8:9], 0, v23
	s_nop 1
	v_cndmask_b32_e64 v23, v24, v28, s[8:9]
	v_mul_f32_e32 v28, 0x37800000, v23
	v_cndmask_b32_e64 v23, v23, v28, s[6:7]
	v_cmp_class_f32_e64 s[6:7], v22, v161
	ds_read_b32 v24, v48 offset:17280
	s_waitcnt lgkmcnt(0)
	v_mul_f32_e32 v16, v24, v16
	v_cndmask_b32_e64 v22, v23, v22, s[6:7]
	v_add_f32_e32 v23, v88, v25
	v_mul_f32_e32 v23, 0xbfb8aa3b, v23
	v_exp_f32_e32 v23, v23
	v_mul_f32_e32 v16, v16, v22
	v_cndmask_b32_e32 v16, 0, v16, vcc
	ds_write_b32 v48, v21 offset:128
	ds_write_b32 v48, v16 offset:33664
	v_add_f32_e32 v22, 1.0, v23
	v_rcp_f32_e32 v22, v22
	v_add_f32_e32 v16, 1.0, v17
	v_rcp_f32_e32 v16, v16
	v_mul_f32_e32 v22, 0xc1000000, v22
	v_mul_f32_e32 v22, v20, v22
	v_add_f32_e32 v23, v22, v22
	v_mul_f32_e32 v23, 0x3fb8aa3b, v23
	v_exp_f32_e32 v23, v23
	v_mul_f32_e32 v22, 0x3fb8aa3b, v22
	v_exp_f32_e32 v22, v22
	v_sub_f32_e32 v17, 1.0, v23
	v_mul_f32_e32 v21, 0x4f800000, v17
	v_cmp_gt_f32_e64 s[6:7], s16, v17
	s_nop 1
	v_cndmask_b32_e64 v17, v17, v21, s[6:7]
	v_sqrt_f32_e32 v21, v17
	s_nop 0
	v_add_u32_e32 v23, -1, v21
	v_fma_f32 v24, -v23, v21, v17
	v_cmp_ge_f32_e64 s[8:9], 0, v24
	v_add_u32_e32 v24, 1, v21
	s_nop 0
	v_cndmask_b32_e64 v23, v21, v23, s[8:9]
	v_fma_f32 v21, -v24, v21, v17
	v_cmp_lt_f32_e64 s[8:9], 0, v21
	s_nop 1
	v_cndmask_b32_e64 v21, v23, v24, s[8:9]
	v_mul_f32_e32 v24, 0x37800000, v21
	v_cndmask_b32_e64 v21, v21, v24, s[6:7]
	v_cmp_class_f32_e64 s[6:7], v17, v161
	ds_read_b32 v23, v49 offset:17280
	s_waitcnt lgkmcnt(0)
	v_mul_f32_e32 v16, v23, v16
	v_cndmask_b32_e64 v17, v21, v17, s[6:7]
	v_add_f32_e32 v21, v88, v26
	v_mul_f32_e32 v21, 0xbfb8aa3b, v21
	v_exp_f32_e32 v21, v21
	v_mul_f32_e32 v16, v16, v17
	v_cndmask_b32_e64 v17, 1.0, v22, s[0:1]
	v_cndmask_b32_e64 v16, 0, v16, s[0:1]
	v_add_f32_e32 v21, 1.0, v21
	v_rcp_f32_e32 v21, v21
	ds_write_b32 v49, v17 offset:128
	ds_write_b32 v49, v16 offset:33664
	v_add_f32_e32 v16, 1.0, v18
	v_rcp_f32_e32 v16, v16
	v_mul_f32_e32 v21, 0xc1000000, v21
	v_mul_f32_e32 v21, v20, v21
	v_add_f32_e32 v22, v21, v21
	v_mul_f32_e32 v22, 0x3fb8aa3b, v22
	v_exp_f32_e32 v22, v22
	v_mul_f32_e32 v21, 0x3fb8aa3b, v21
	v_exp_f32_e32 v21, v21
	v_sub_f32_e32 v17, 1.0, v22
	v_mul_f32_e32 v18, 0x4f800000, v17
	v_cmp_gt_f32_e64 s[6:7], s16, v17
	s_nop 1
	v_cndmask_b32_e64 v17, v17, v18, s[6:7]
	v_sqrt_f32_e32 v18, v17
	s_nop 0
	v_add_u32_e32 v22, -1, v18
	v_fma_f32 v23, -v22, v18, v17
	v_cmp_ge_f32_e64 s[8:9], 0, v23
	v_add_u32_e32 v23, 1, v18
	s_nop 0
	v_cndmask_b32_e64 v22, v18, v22, s[8:9]
	v_fma_f32 v18, -v23, v18, v17
	v_cmp_lt_f32_e64 s[8:9], 0, v18
	s_nop 1
	v_cndmask_b32_e64 v18, v22, v23, s[8:9]
	v_mul_f32_e32 v23, 0x37800000, v18
	v_cndmask_b32_e64 v18, v18, v23, s[6:7]
	v_cmp_class_f32_e64 s[6:7], v17, v161
	ds_read_b32 v22, v50 offset:17280
	s_waitcnt lgkmcnt(0)
	v_mul_f32_e32 v16, v16, v22
	v_cndmask_b32_e64 v17, v18, v17, s[6:7]
	v_add_f32_e32 v18, v88, v27
	v_mul_f32_e32 v18, 0xbfb8aa3b, v18
	v_exp_f32_e32 v18, v18
	v_mul_f32_e32 v16, v16, v17
	v_cndmask_b32_e64 v17, 1.0, v21, s[2:3]
	v_cndmask_b32_e64 v16, 0, v16, s[2:3]
	v_add_f32_e32 v18, 1.0, v18
	v_rcp_f32_e32 v18, v18
	ds_write_b32 v50, v17 offset:128
	ds_write_b32 v50, v16 offset:33664
	v_add_f32_e32 v16, 1.0, v19
	v_rcp_f32_e32 v16, v16
	v_mul_f32_e32 v18, 0xc1000000, v18
	v_mul_f32_e32 v18, v20, v18
	v_add_f32_e32 v20, v18, v18
	v_mul_f32_e32 v20, 0x3fb8aa3b, v20
	v_exp_f32_e32 v20, v20
	v_mul_f32_e32 v18, 0x3fb8aa3b, v18
	v_exp_f32_e32 v18, v18
	v_sub_f32_e32 v17, 1.0, v20
	v_mul_f32_e32 v19, 0x4f800000, v17
	v_cmp_gt_f32_e64 s[6:7], s16, v17
	v_cndmask_b32_e64 v14, 1.0, v18, s[4:5]
	s_nop 0
	v_cndmask_b32_e64 v17, v17, v19, s[6:7]
	v_sqrt_f32_e32 v19, v17
	s_nop 0
	v_add_u32_e32 v20, -1, v19
	v_fma_f32 v21, -v20, v19, v17
	v_cmp_ge_f32_e64 s[8:9], 0, v21
	v_add_u32_e32 v21, 1, v19
	s_nop 0
	v_cndmask_b32_e64 v20, v19, v20, s[8:9]
	v_fma_f32 v19, -v21, v19, v17
	v_cmp_lt_f32_e64 s[8:9], 0, v19
	s_nop 1
	v_cndmask_b32_e64 v19, v20, v21, s[8:9]
	ds_read_b32 v21, v51 offset:17280
	v_mul_f32_e32 v20, 0x37800000, v19
	v_cndmask_b32_e64 v19, v19, v20, s[6:7]
	v_cmp_class_f32_e64 s[6:7], v17, v161
	s_waitcnt lgkmcnt(0)
; DI float sigm(float x) { return __builtin_amdgcn_rcpf(1.f + __expf(-x)); }
; DI void lru_tile(const Params& p, int layer, int isP, int sq, int tile, int nb, int pass, char*) {
;     ...
;       const float bav = pbav[nt], bxv = pbxv[nt];
;       const float sp = log1pf(__expf(-plam[nt]));
; #pragma unroll
;       for (int j = 0; j < 4; ++j) {
;         const int t = wid * 16 + fq * 4 + j;
;         float r = sigm(ar[j] + bav), ig = sigm(ai[j] + bxv);
;         float la = -8.f * r * sp;
;         float a = __expf(la);
;         float b = sqrtf(1.f - __expf(2.f * la)) * (ig * xcs[t * 64 + d]);
;         if (t0 + t >= T) { a = 1.f; b = 0.f; }
;         as_[t * 64 + d] = a;
;         bs_[t * 64 + d] = b;
;       }
;     }
	v_mul_f32_e32 v13, v16, v21
	v_cndmask_b32_e64 v12, v19, v17, s[6:7]
	v_mul_f32_e32 v12, v12, v13
	v_mul_f32_e32 v13, 0xbfb8aa3b, v86
	v_exp_f32_e32 v13, v13
	v_cndmask_b32_e64 v12, 0, v12, s[4:5]
	ds_write_b32 v51, v14 offset:128
	ds_write_b32 v51, v12 offset:33664
	v_add_f32_e32 v6, 1.0, v13
	v_add_f32_e32 v4, -1.0, v6
	v_sub_f32_e32 v5, v4, v6
	v_add_f32_e32 v5, 1.0, v5
	v_sub_f32_e32 v4, v13, v4
	v_add_f32_e32 v7, v4, v5
	v_frexp_mant_f32_e32 v15, v6
	v_cvt_f64_f32_e32 v[4:5], v6
	v_frexp_exp_i32_f64_e32 v4, v[4:5]
	v_cmp_gt_f32_e64 s[6:7], s12, v15
	s_nop 1
	v_subbrev_co_u32_e64 v4, s[6:7], 0, v4, s[6:7]
	v_sub_u32_e32 v5, 0, v4
	v_ldexp_f32 v6, v6, v5
	v_ldexp_f32 v5, v7, v5
	v_add_f32_e32 v7, -1.0, v6
	v_add_f32_e32 v17, 1.0, v6
	v_add_f32_e32 v15, 1.0, v7
	v_add_f32_e32 v18, -1.0, v17
	v_sub_f32_e32 v15, v6, v15
	v_sub_f32_e32 v6, v6, v18
	v_add_f32_e32 v15, v5, v15
	v_add_f32_e32 v5, v5, v6
	v_add_f32_e32 v6, v17, v5
	v_rcp_f32_e32 v18, v6
	v_add_f32_e32 v16, v7, v15
	v_sub_f32_e32 v7, v16, v7
	v_sub_f32_e32 v7, v15, v7
	v_sub_f32_e32 v15, v6, v17
	v_sub_f32_e32 v5, v5, v15
	v_mul_f32_e32 v15, v16, v18
	v_mul_f32_e32 v17, v6, v15
	v_fma_f32 v19, v15, v6, -v17
	v_fmac_f32_e32 v19, v15, v5
	v_add_f32_e32 v20, v17, v19
	v_sub_f32_e32 v21, v16, v20
	v_sub_f32_e32 v16, v16, v21
	v_sub_f32_e32 v17, v20, v17
	v_sub_f32_e32 v16, v16, v20
	v_add_f32_e32 v7, v7, v16
	v_sub_f32_e32 v16, v17, v19
	v_add_f32_e32 v7, v16, v7
	v_add_f32_e32 v16, v21, v7
	v_mul_f32_e32 v17, v18, v16
	v_mul_f32_e32 v19, v6, v17
	v_fma_f32 v6, v17, v6, -v19
	v_fmac_f32_e32 v6, v17, v5
	v_sub_f32_e32 v5, v21, v16
	v_add_f32_e32 v5, v7, v5
	v_add_f32_e32 v7, v19, v6
	v_sub_f32_e32 v20, v16, v7
	v_sub_f32_e32 v16, v16, v20
	v_sub_f32_e32 v19, v7, v19
	v_sub_f32_e32 v7, v16, v7
	v_add_f32_e32 v5, v5, v7
	v_sub_f32_e32 v6, v19, v6
	v_cvt_f32_i32_e32 v4, v4
	v_add_f32_e32 v5, v6, v5
	v_add_f32_e32 v6, v15, v17
	v_add_f32_e32 v5, v20, v5
	v_sub_f32_e32 v7, v6, v15
	v_mul_f32_e32 v5, v18, v5
	v_sub_f32_e32 v7, v17, v7
	v_add_f32_e32 v5, v7, v5
	v_mul_f32_e32 v17, 0x3f317218, v4
	v_add_f32_e32 v7, v6, v5
	v_fma_f32 v18, v4, s13, -v17
	v_mul_f32_e32 v15, v7, v7
	v_fmac_f32_e32 v18, 0xb102e308, v4
	v_sub_f32_e32 v4, v7, v6
	v_fmamk_f32 v16, v15, 0x3e9b6dac, v160
	v_sub_f32_e32 v4, v5, v4
	v_add_f32_e32 v5, v17, v18
	v_fmaak_f32 v16, v15, v16, 0x3f2aaada
	v_sub_f32_e32 v6, v5, v17
	v_ldexp_f32 v17, v7, 1
	v_mul_f32_e32 v7, v7, v15
	v_mul_f32_e32 v7, v7, v16
	v_add_f32_e32 v15, v17, v7
	v_sub_f32_e32 v16, v15, v17
	v_ldexp_f32 v4, v4, 1
	v_sub_f32_e32 v7, v7, v16
	v_add_f32_e32 v4, v4, v7
	v_add_f32_e32 v7, v15, v4
	v_sub_f32_e32 v15, v7, v15
	v_sub_f32_e32 v4, v4, v15
	v_add_f32_e32 v15, v5, v7
	v_sub_f32_e32 v16, v15, v5
	v_sub_f32_e32 v17, v15, v16
	v_sub_f32_e32 v6, v18, v6
	v_sub_f32_e32 v5, v5, v17
	v_sub_f32_e32 v7, v7, v16
	v_add_f32_e32 v5, v7, v5
	v_add_f32_e32 v7, v6, v4
	v_sub_f32_e32 v16, v7, v6
	v_sub_f32_e32 v17, v7, v16
	v_sub_f32_e32 v6, v6, v17
	v_sub_f32_e32 v4, v4, v16
	v_add_f32_e32 v5, v7, v5
	v_add_f32_e32 v4, v4, v6
	v_add_f32_e32 v6, v15, v5
	v_sub_f32_e32 v7, v6, v15
	v_sub_f32_e32 v5, v5, v7
	v_add_f32_e32 v4, v4, v5
	v_add_f32_e32 v5, v85, v8
	v_mul_f32_e32 v5, 0xbfb8aa3b, v5
	v_exp_f32_e32 v5, v5
	v_add_f32_e32 v4, v6, v4
	v_cmp_neq_f32_e64 s[6:7], s14, v13
	v_add_f32_e32 v5, 1.0, v5
	v_rcp_f32_e32 v5, v5
	v_cndmask_b32_e64 v4, v177, v4, s[6:7]
	v_cmp_ngt_f32_e64 s[6:7], -1.0, v13
	v_mul_f32_e32 v5, 0xc1000000, v5
	s_nop 0
	v_cndmask_b32_e64 v4, v178, v4, s[6:7]
	v_cmp_neq_f32_e64 s[6:7], -1.0, v13
	s_nop 1
	v_cndmask_b32_e64 v4, v179, v4, s[6:7]
	v_cmp_lt_f32_e64 s[6:7], |v13|, s15
	s_nop 1
	v_cndmask_b32_e64 v4, v4, v13, s[6:7]
	v_mul_f32_e32 v5, v4, v5
	v_add_f32_e32 v6, v5, v5
	v_mul_f32_e32 v6, 0x3fb8aa3b, v6
	v_exp_f32_e32 v6, v6
	v_mul_f32_e32 v5, 0x3fb8aa3b, v5
	v_exp_f32_e32 v5, v5
	v_sub_f32_e32 v6, 1.0, v6
	v_mul_f32_e32 v7, 0x4f800000, v6
	v_cmp_gt_f32_e64 s[6:7], s16, v6
	v_cndmask_b32_e32 v5, 1.0, v5, vcc
	s_nop 0
	v_cndmask_b32_e64 v6, v6, v7, s[6:7]
	v_sqrt_f32_e32 v7, v6
	s_nop 0
	v_add_u32_e32 v8, -1, v7
	v_fma_f32 v12, -v8, v7, v6
	v_cmp_ge_f32_e64 s[8:9], 0, v12
	v_add_u32_e32 v12, 1, v7
	s_nop 0
	v_cndmask_b32_e64 v8, v7, v8, s[8:9]
	v_fma_f32 v7, -v12, v7, v6
	v_cmp_lt_f32_e64 s[8:9], 0, v7
	s_nop 1
	v_cndmask_b32_e64 v7, v8, v12, s[8:9]
	v_mul_f32_e32 v12, 0x37800000, v7
	v_cndmask_b32_e64 v7, v7, v12, s[6:7]
	v_cmp_class_f32_e64 s[6:7], v6, v161
	ds_read_b32 v8, v48 offset:17344
	s_waitcnt lgkmcnt(0)
	v_mul_f32_e32 v0, v8, v0
	v_cndmask_b32_e64 v6, v7, v6, s[6:7]
	v_add_f32_e32 v7, v85, v9
	v_mul_f32_e32 v7, 0xbfb8aa3b, v7
	v_exp_f32_e32 v7, v7
	v_mul_f32_e32 v0, v0, v6
	v_cndmask_b32_e32 v0, 0, v0, vcc
	ds_write_b32 v48, v5 offset:192
	ds_write_b32 v48, v0 offset:33728
	v_add_f32_e32 v6, 1.0, v7
	v_rcp_f32_e32 v6, v6
	v_add_f32_e32 v0, 1.0, v1
	v_rcp_f32_e32 v0, v0
	v_mul_f32_e32 v6, 0xc1000000, v6
	v_mul_f32_e32 v6, v4, v6
	v_add_f32_e32 v7, v6, v6
	v_mul_f32_e32 v7, 0x3fb8aa3b, v7
	v_exp_f32_e32 v7, v7
	v_mul_f32_e32 v6, 0x3fb8aa3b, v6
	v_exp_f32_e32 v6, v6
	v_sub_f32_e32 v1, 1.0, v7
	v_mul_f32_e32 v5, 0x4f800000, v1
	v_cmp_gt_f32_e32 vcc, s16, v1
	s_nop 1
	v_cndmask_b32_e32 v1, v1, v5, vcc
	v_sqrt_f32_e32 v5, v1
	s_nop 0
	v_add_u32_e32 v7, -1, v5
	v_fma_f32 v8, -v7, v5, v1
	v_cmp_ge_f32_e64 s[6:7], 0, v8
	v_add_u32_e32 v8, 1, v5
	s_nop 0
	v_cndmask_b32_e64 v7, v5, v7, s[6:7]
	v_fma_f32 v5, -v8, v5, v1
	v_cmp_lt_f32_e64 s[6:7], 0, v5
	s_nop 1
	v_cndmask_b32_e64 v5, v7, v8, s[6:7]
	v_mul_f32_e32 v8, 0x37800000, v5
	v_cndmask_b32_e32 v5, v5, v8, vcc
	v_cmp_class_f32_e32 vcc, v1, v161
	ds_read_b32 v7, v49 offset:17344
	s_waitcnt lgkmcnt(0)
; DI float sigm(float x) { return __builtin_amdgcn_rcpf(1.f + __expf(-x)); }
; DI void lru_tile(const Params& p, int layer, int isP, int sq, int tile, int nb, int pass, char*) {
;     ...
;       for (int j = 0; j < 4; ++j) {
;         const int t = wid * 16 + fq * 4 + j;
;         float r = sigm(ar[j] + bav), ig = sigm(ai[j] + bxv);
;         float la = -8.f * r * sp;
;         float a = __expf(la);
;         float b = sqrtf(1.f - __expf(2.f * la)) * (ig * xcs[t * 64 + d]);
;         if (t0 + t >= T) { a = 1.f; b = 0.f; }
;         as_[t * 64 + d] = a;
;         bs_[t * 64 + d] = b;
;       }
;     }
;   }
;   __syncthreads();
;   const int c = tid & 63;
;   {
;     float A = 1.f, B = 0.f;
; #pragma unroll
;     for (int tt = 0; tt < 16; ++tt) {
;       float a = as_[(wid * 16 + tt) * 64 + c], b = bs_[(wid * 16 + tt) * 64 + c];
;       A *= a; B = a * B + b;
;     }
;     ab[(wid * 64 + c) * 2] = A;
;     ab[(wid * 64 + c) * 2 + 1] = B;
;   }
;   __syncthreads();
	v_mul_f32_e32 v0, v7, v0
	v_cndmask_b32_e32 v1, v5, v1, vcc
	v_add_f32_e32 v5, v85, v10
	v_mul_f32_e32 v5, 0xbfb8aa3b, v5
	v_exp_f32_e32 v5, v5
	v_mul_f32_e32 v0, v0, v1
	v_cndmask_b32_e64 v1, 1.0, v6, s[0:1]
	v_cndmask_b32_e64 v0, 0, v0, s[0:1]
	v_add_f32_e32 v5, 1.0, v5
	v_rcp_f32_e32 v5, v5
	ds_write_b32 v49, v1 offset:192
	ds_write_b32 v49, v0 offset:33728
	v_add_f32_e32 v0, 1.0, v2
	v_rcp_f32_e32 v0, v0
	v_mul_f32_e32 v5, 0xc1000000, v5
	v_mul_f32_e32 v5, v4, v5
	v_add_f32_e32 v6, v5, v5
	v_mul_f32_e32 v6, 0x3fb8aa3b, v6
	v_exp_f32_e32 v6, v6
	v_mul_f32_e32 v5, 0x3fb8aa3b, v5
	v_exp_f32_e32 v5, v5
	v_sub_f32_e32 v1, 1.0, v6
	v_mul_f32_e32 v2, 0x4f800000, v1
	v_cmp_gt_f32_e32 vcc, s16, v1
	s_nop 1
	v_cndmask_b32_e32 v1, v1, v2, vcc
	v_sqrt_f32_e32 v2, v1
	s_nop 0
	v_add_u32_e32 v6, -1, v2
	v_fma_f32 v7, -v6, v2, v1
	v_cmp_ge_f32_e64 s[0:1], 0, v7
	v_add_u32_e32 v7, 1, v2
	s_nop 0
	v_cndmask_b32_e64 v6, v2, v6, s[0:1]
	v_fma_f32 v2, -v7, v2, v1
	v_cmp_lt_f32_e64 s[0:1], 0, v2
	s_nop 1
	v_cndmask_b32_e64 v2, v6, v7, s[0:1]
	v_mul_f32_e32 v7, 0x37800000, v2
	v_cndmask_b32_e32 v2, v2, v7, vcc
	v_cmp_class_f32_e32 vcc, v1, v161
	ds_read_b32 v6, v50 offset:17344
	s_waitcnt lgkmcnt(0)
	v_mul_f32_e32 v0, v0, v6
	v_cndmask_b32_e32 v1, v2, v1, vcc
	v_add_f32_e32 v2, v85, v11
	v_mul_f32_e32 v2, 0xbfb8aa3b, v2
	v_exp_f32_e32 v2, v2
	v_mul_f32_e32 v0, v0, v1
	v_cndmask_b32_e64 v1, 1.0, v5, s[2:3]
	v_cndmask_b32_e64 v0, 0, v0, s[2:3]
	v_add_f32_e32 v2, 1.0, v2
	v_rcp_f32_e32 v2, v2
	ds_write_b32 v50, v1 offset:192
	ds_write_b32 v50, v0 offset:33728
	v_add_f32_e32 v0, 1.0, v3
	v_rcp_f32_e32 v0, v0
	v_mul_f32_e32 v2, 0xc1000000, v2
	v_mul_f32_e32 v2, v4, v2
	v_add_f32_e32 v4, v2, v2
	v_mul_f32_e32 v4, 0x3fb8aa3b, v4
	v_exp_f32_e32 v4, v4
	v_mul_f32_e32 v2, 0x3fb8aa3b, v2
	v_exp_f32_e32 v2, v2
	v_sub_f32_e32 v1, 1.0, v4
	v_mul_f32_e32 v3, 0x4f800000, v1
	v_cmp_gt_f32_e32 vcc, s16, v1
	s_nop 1
	v_cndmask_b32_e32 v1, v1, v3, vcc
	v_sqrt_f32_e32 v3, v1
	s_nop 0
	v_add_u32_e32 v4, -1, v3
	v_fma_f32 v5, -v4, v3, v1
	v_cmp_ge_f32_e64 s[0:1], 0, v5
	v_add_u32_e32 v5, 1, v3
	s_nop 0
	v_cndmask_b32_e64 v4, v3, v4, s[0:1]
	v_fma_f32 v3, -v5, v3, v1
	v_cmp_lt_f32_e64 s[0:1], 0, v3
	s_nop 1
	v_cndmask_b32_e64 v3, v4, v5, s[0:1]
	ds_read_b32 v4, v51 offset:17344
	v_mul_f32_e32 v5, 0x37800000, v3
	v_cndmask_b32_e32 v3, v3, v5, vcc
	v_cmp_class_f32_e32 vcc, v1, v161
	s_lshl_b32 s0, s47, 9
	s_waitcnt lgkmcnt(0)
	v_mul_f32_e32 v0, v0, v4
	v_cndmask_b32_e32 v1, v3, v1, vcc
	v_mul_f32_e32 v0, v1, v0
	v_cndmask_b32_e64 v1, 1.0, v2, s[4:5]
	v_cndmask_b32_e64 v0, 0, v0, s[4:5]
	ds_write_b32 v51, v1 offset:192
	ds_write_b32 v51, v0 offset:33728
	v_lshlrev_b32_e32 v0, 2, v72
	v_lshl_or_b32 v1, s47, 12, v0
	v_add_u32_e32 v1, 0x80, v1
	s_waitcnt lgkmcnt(0)
	s_barrier
	ds_read2st64_b32 v[2:3], v1 offset0:131 offset1:132
	ds_read2st64_b32 v[4:5], v1 offset1:1
	ds_read2st64_b32 v[6:7], v1 offset0:2 offset1:3
	ds_read2st64_b32 v[8:9], v1 offset0:4 offset1:5
	ds_read2st64_b32 v[10:11], v1 offset0:6 offset1:7
	ds_read2st64_b32 v[12:13], v1 offset0:133 offset1:134
	ds_read2st64_b32 v[14:15], v1 offset0:135 offset1:136
	ds_read2st64_b32 v[16:17], v1 offset0:137 offset1:138
	s_waitcnt lgkmcnt(6)
	v_fma_f32 v18, 0, v4, v2
	v_fmac_f32_e32 v3, v18, v5
	s_waitcnt lgkmcnt(2)
	v_fma_f32 v3, v3, v6, v12
	v_fmac_f32_e32 v13, v3, v7
	s_waitcnt lgkmcnt(1)
	v_fma_f32 v3, v13, v8, v14
	v_fmac_f32_e32 v15, v3, v9
	s_waitcnt lgkmcnt(0)
	v_fma_f32 v3, v15, v10, v16
	v_mul_f32_e32 v2, v4, v5
	v_fmac_f32_e32 v17, v3, v11
	ds_read2st64_b32 v[4:5], v1 offset0:139 offset1:140
	ds_read2st64_b32 v[12:13], v1 offset0:8 offset1:9
	ds_read2st64_b32 v[14:15], v1 offset0:10 offset1:11
	ds_read2st64_b32 v[18:19], v1 offset0:12 offset1:13
	ds_read2st64_b32 v[20:21], v1 offset0:14 offset1:15
	ds_read2st64_b32 v[22:23], v1 offset0:141 offset1:142
	ds_read2st64_b32 v[24:25], v1 offset0:143 offset1:144
	ds_read2st64_b32 v[26:27], v1 offset0:145 offset1:146
	s_waitcnt lgkmcnt(6)
	v_fmac_f32_e32 v4, v17, v12
	v_mov_b32_e32 v3, v4
	v_mov_b32_e32 v16, v6
	v_mov_b32_e32 v17, v13
	v_mov_b32_e32 v4, v7
	v_mul_f32_e32 v6, v2, v6
	v_pk_fma_f32 v[2:3], v[2:3], v[16:17], v[4:5]
	v_mul_f32_e32 v6, v6, v7
	v_mov_b32_e32 v7, v3
	v_mov_b32_e32 v2, v8
	s_waitcnt lgkmcnt(5)
	v_mov_b32_e32 v3, v14
	v_pk_mul_f32 v[4:5], v[6:7], v[2:3]
	v_mov_b32_e32 v8, v9
	v_mov_b32_e32 v16, v9
	s_waitcnt lgkmcnt(2)
	v_mov_b32_e32 v17, v22
	v_pk_mul_f32 v[4:5], v[4:5], v[8:9]
	v_pk_fma_f32 v[2:3], v[6:7], v[2:3], v[16:17]
	s_addk_i32 s0, 0x80
	v_mov_b32_e32 v2, v4
	v_lshl_add_u32 v9, v128, 2, s0
	v_mov_b32_e32 v6, v10
	v_mov_b32_e32 v7, v15
	v_pk_mul_f32 v[4:5], v[4:5], v[10:11]
	v_mov_b32_e32 v8, v11
	v_mov_b32_e32 v22, v11
	v_pk_mul_f32 v[4:5], v[4:5], v[8:9]
	v_pk_fma_f32 v[2:3], v[2:3], v[6:7], v[22:23]
	v_mov_b32_e32 v8, v13
	v_mov_b32_e32 v5, v3
	v_mov_b32_e32 v2, v12
	v_mov_b32_e32 v3, v18
	v_pk_mul_f32 v[6:7], v[4:5], v[2:3]
	v_mov_b32_e32 v10, v13
	s_waitcnt lgkmcnt(1)
	v_mov_b32_e32 v11, v24
	v_pk_mul_f32 v[6:7], v[6:7], v[8:9]
	v_pk_fma_f32 v[2:3], v[4:5], v[2:3], v[10:11]
	v_mov_b32_e32 v4, v14
	v_mov_b32_e32 v2, v6
	v_mov_b32_e32 v5, v19
	v_pk_mul_f32 v[6:7], v[6:7], v[14:15]
	v_mov_b32_e32 v8, v15
	v_mov_b32_e32 v24, v15
	v_pk_mul_f32 v[6:7], v[6:7], v[8:9]
	v_pk_fma_f32 v[2:3], v[2:3], v[4:5], v[24:25]
	v_mov_b32_e32 v8, v19
	v_mov_b32_e32 v7, v3
	v_mov_b32_e32 v2, v18
	v_mov_b32_e32 v3, v20
	v_pk_mul_f32 v[4:5], v[6:7], v[2:3]
	v_mov_b32_e32 v10, v19
	s_waitcnt lgkmcnt(0)
	v_mov_b32_e32 v11, v26
	v_pk_mul_f32 v[4:5], v[4:5], v[8:9]
	v_pk_fma_f32 v[2:3], v[6:7], v[2:3], v[10:11]
	v_mov_b32_e32 v6, v21
	v_mov_b32_e32 v2, v4
	v_pk_mul_f32 v[4:5], v[4:5], v[20:21]
	v_mov_b32_e32 v26, v21
	v_pk_mul_f32 v[4:5], v[4:5], v[6:7]
	v_pk_fma_f32 v[2:3], v[2:3], v[20:21], v[26:27]
	s_cmp_gt_i32 s45, 0
	v_mov_b32_e32 v5, v3
	ds_write_b64 v9, v[4:5] offset:49920
	s_waitcnt lgkmcnt(0)
	s_barrier
; DI void lru_tile(const Params& p, int layer, int isP, int sq, int tile, int nb, int pass, char*) {
;     ...
;     float h = isP ? 0.f : p.state_lru[(long)(layer * NB_S + sq) * 512 + ch0 + c];
;     for (int i0 = 0; i0 < tile; i0 += 16) {
;       float2 e[16];
; #pragma unroll
;       for (int u = 0; u < 16; ++u)
;         e[u] = (i0 + u < tile) ? *(const float2*)(agg + ((long)(sq * NTILE_P + i0 + u) * 512 + ch0 + c) * 2) : make_float2(1.f, 0.f);
; #pragma unroll
;       for (int u = 0; u < 16; ++u) h = e[u].x * h + e[u].y;
;     }
;     for (int w = 0; w < wid; ++w) h = ab[(w * 64 + c) * 2] * h + ab[(w * 64 + c) * 2 + 1];
	s_cbranch_scc0 .LBB0_4794
	s_mul_i32 s0, s42, 0x41
	s_ashr_i32 s1, s0, 31
	s_lshl_b64 s[0:1], s[0:1], 12
	s_add_u32 s0, s63, s0
	v_lshlrev_b32_e32 v2, 3, v75
	v_mov_b32_e32 v3, v129
	s_addc_u32 s1, s88, s1
	v_lshl_add_u64 v[2:3], s[0:1], 0, v[2:3]
	v_mov_b32_e32 v36, 0
	s_waitcnt vmcnt(0)
	v_fma_f32 v36, v36, v132, v133
	s_cmpk_lt_i32 s45, 2
	s_cbranch_scc1 .LBB0_4795
	v_fma_f32 v36, v36, v134, v135
	s_cmpk_lt_i32 s45, 3
	s_cbranch_scc1 .LBB0_4795
	v_fma_f32 v36, v36, v136, v137
	s_cmpk_lt_i32 s45, 4
	s_cbranch_scc1 .LBB0_4795
	v_fma_f32 v36, v36, v138, v139
	s_cmpk_lt_i32 s45, 5
	s_cbranch_scc1 .LBB0_4795
	v_fma_f32 v36, v36, v140, v141
	s_cmpk_lt_i32 s45, 6
	s_cbranch_scc1 .LBB0_4795
	v_fma_f32 v36, v36, v142, v143
	s_cmpk_lt_i32 s45, 7
	s_cbranch_scc1 .LBB0_4795
	v_fma_f32 v36, v36, v144, v145
	s_cmpk_lt_i32 s45, 8
	s_cbranch_scc1 .LBB0_4795
	v_fma_f32 v36, v36, v146, v147
	s_cmpk_lt_i32 s45, 9
	s_cbranch_scc1 .LBB0_4795
	v_fma_f32 v36, v36, v148, v149
	s_cmpk_lt_i32 s45, 10
	s_cbranch_scc1 .LBB0_4795
	v_fma_f32 v36, v36, v150, v151
	s_cmpk_lt_i32 s45, 11
	s_cbranch_scc1 .LBB0_4795
	v_fma_f32 v36, v36, v152, v153
	s_cmpk_lt_i32 s45, 12
	s_cbranch_scc1 .LBB0_4795
	v_fma_f32 v36, v36, v154, v155
	s_cmpk_lt_i32 s45, 13
	s_cbranch_scc1 .LBB0_4795
	v_fma_f32 v36, v36, v156, v157
	s_cmpk_lt_i32 s45, 14
	s_cbranch_scc1 .LBB0_4795
	v_fma_f32 v36, v36, v180, v181
	s_cmpk_lt_i32 s45, 15
	s_cbranch_scc1 .LBB0_4795
	v_fma_f32 v36, v36, v182, v183
	s_cmpk_lt_i32 s45, 16
	s_cbranch_scc1 .LBB0_4795
	v_fma_f32 v36, v36, v184, v185
	s_cmpk_lt_i32 s45, 17
	s_cbranch_scc1 .LBB0_4795
	v_fma_f32 v36, v36, v186, v187
	s_cmpk_lt_i32 s45, 18
	s_cbranch_scc1 .LBB0_4795
	v_fma_f32 v36, v36, v188, v189
	s_cmpk_lt_i32 s45, 19
	s_cbranch_scc1 .LBB0_4795
	v_fma_f32 v36, v36, v190, v191
	s_cmpk_lt_i32 s45, 20
	s_cbranch_scc1 .LBB0_4795
	v_fma_f32 v36, v36, v192, v193
	s_cmpk_lt_i32 s45, 21
	s_cbranch_scc1 .LBB0_4795
	v_fma_f32 v36, v36, v194, v195
	s_cmpk_lt_i32 s45, 22
	s_cbranch_scc1 .LBB0_4795
	v_fma_f32 v36, v36, v196, v197
	s_cmpk_lt_i32 s45, 23
	s_cbranch_scc1 .LBB0_4795
	v_fma_f32 v36, v36, v198, v199
	s_cmpk_lt_i32 s45, 24
	s_cbranch_scc1 .LBB0_4795
	v_fma_f32 v36, v36, v200, v201
	s_cmpk_lt_i32 s45, 25
	s_cbranch_scc1 .LBB0_4795
	v_fma_f32 v36, v36, v202, v203
	s_cmpk_lt_i32 s45, 26
	s_cbranch_scc1 .LBB0_4795
	v_fma_f32 v36, v36, v204, v205
	s_cmpk_lt_i32 s45, 27
	s_cbranch_scc1 .LBB0_4795
	v_fma_f32 v36, v36, v206, v207
	s_cmpk_lt_i32 s45, 28
	s_cbranch_scc1 .LBB0_4795
	v_fma_f32 v36, v36, v208, v209
	s_cmpk_lt_i32 s45, 29
	s_cbranch_scc1 .LBB0_4795
	v_fma_f32 v36, v36, v210, v211
	s_cmpk_lt_i32 s45, 30
	s_cbranch_scc1 .LBB0_4795
	v_fma_f32 v36, v36, v212, v213
	s_cmpk_lt_i32 s45, 31
	s_cbranch_scc1 .LBB0_4795
	v_fma_f32 v36, v36, v214, v215
	s_cmpk_lt_i32 s45, 32
	s_cbranch_scc1 .LBB0_4795
	v_fma_f32 v36, v36, v216, v217
	s_cmpk_lt_i32 s45, 33
	s_cbranch_scc1 .LBB0_4795
	v_fma_f32 v36, v36, v218, v219
	s_cmpk_lt_i32 s45, 34
	s_cbranch_scc1 .LBB0_4795
	v_fma_f32 v36, v36, v220, v221
	s_cmpk_lt_i32 s45, 35
	s_cbranch_scc1 .LBB0_4795
	v_fma_f32 v36, v36, v222, v223
	s_cmpk_lt_i32 s45, 36
	s_cbranch_scc1 .LBB0_4795
	v_fma_f32 v36, v36, v224, v225
	s_cmpk_lt_i32 s45, 37
	s_cbranch_scc1 .LBB0_4795
	v_fma_f32 v36, v36, v226, v227
	s_cmpk_lt_i32 s45, 38
	s_cbranch_scc1 .LBB0_4795
	v_fma_f32 v36, v36, v228, v229
	s_cmpk_lt_i32 s45, 39
	s_cbranch_scc1 .LBB0_4795
	v_fma_f32 v36, v36, v230, v231
	s_cmpk_lt_i32 s45, 40
	s_cbranch_scc1 .LBB0_4795
	v_fma_f32 v36, v36, v232, v233
	s_cmpk_lt_i32 s45, 41
	s_cbranch_scc1 .LBB0_4795
	v_fma_f32 v36, v36, v234, v235
	s_cmpk_lt_i32 s45, 42
	s_cbranch_scc1 .LBB0_4795
	v_fma_f32 v36, v36, v236, v237
	s_cmpk_lt_i32 s45, 43
	s_cbranch_scc1 .LBB0_4795
	v_fma_f32 v36, v36, v238, v239
	s_cmpk_lt_i32 s45, 44
	s_cbranch_scc1 .LBB0_4795
	v_fma_f32 v36, v36, v240, v241
	s_cmpk_lt_i32 s45, 45
	s_cbranch_scc1 .LBB0_4795
	v_fma_f32 v36, v36, v242, v243
	s_cmpk_lt_i32 s45, 46
	s_cbranch_scc1 .LBB0_4795
	v_fma_f32 v36, v36, v244, v245
	s_cmpk_lt_i32 s45, 47
	s_cbranch_scc1 .LBB0_4795
	s_movk_i32 s11, 46
	s_mov_b64 s[0:1], 0x2e000
	v_lshl_add_u64 v[2:3], v[2:3], 0, s[0:1]
	s_branch .LBB0_4764

; DI int pop_block(int* ctr, int*) {
;   __syncthreads();
;   if (threadIdx.x == 0) sh_item = atomicAdd(ctr, 1);
;   __syncthreads();
;   return __builtin_amdgcn_readfirstlane(sh_item);
; DI void phase_b2(const Params& p, int layer, char*, int*) {
;     ...
;   for (;;) {
;     int it = pop_block(ctr2, nullptr);
.LBB0_4834:
	s_barrier
	s_and_saveexec_b64 s[0:1], s[96:97]
	s_cbranch_execz .LBB0_4838
	v_readfirstlane_b32 s4, v131
	s_cmp_lg_u32 s4, 0
	s_cbranch_scc1 .Lpf_have_a
	v_mov_b32_e32 v1, 1
	global_atomic_add v1, v129, v1, s[38:39] offset:8 sc0
	s_waitcnt vmcnt(0)
	s_branch .Lpf_map_a

; DI int pop_block(int* ctr, int*) {
;     ...
;   if (threadIdx.x == 0) sh_item = atomicAdd(ctr, 1);
;   __syncthreads();
;   return __builtin_amdgcn_readfirstlane(sh_item);
; DI void phase_b2(const Params& p, int layer, char*, int*) {
;     ...
;   for (;;) {
;     int it = pop_block(ctr2, nullptr);
;     if (it >= 2208) break;
;     if (it < 2048) { const int c = 64 - (it >> 5), pair = it & 31; attn_block(p, 1, pair >> 3, c, pair & 7); }
;     else if (it < 2176) { const int r = it - 2048; attn_block(p, 0, r >> 3, 0, r & 7); }
;     else { const int pair = it - 2176; attn_block(p, 1, pair >> 3, 0, pair & 7); }
.Lpf_map_a:
	v_add_u32_e32 v0, 0x420, v1
	v_subrev_u32_e32 v2, 0x80, v1
	v_cmp_gt_u32_e32 vcc, 0x460, v1
	s_nop 1
	v_cndmask_b32_e32 v0, v2, v0, vcc
	v_cmp_gt_u32_e32 vcc, 0x3e0, v1
	s_nop 1
	v_cndmask_b32_e32 v0, v0, v1, vcc
	v_cmp_gt_u32_e32 vcc, 0x880, v1
	s_nop 1
	v_cndmask_b32_e32 v1, v1, v0, vcc
	ds_write_b32 v129, v1 offset:32

; #define MFMA16(a, b, c) __builtin_amdgcn_mfma_f32_16x16x32_bf16((a), (b), (c), 0, 0, 0)
; DI void attn_block(const Params& p, int isP, int sq, int c, int h) {
;     ...
;       for (int qt = 0; qt < 4; ++qt) {
;         if (qt < nqt) {
;           f32x4 sa = {0.f, 0.f, 0.f, 0.f}, sb = {0.f, 0.f, 0.f, 0.f};
;           sa = MFMA16(ka0, qf[qt][0], sa); sa = MFMA16(ka1, qf[qt][1], sa);
;           sb = MFMA16(kb0, qf[qt][0], sb); sb = MFMA16(kb1, qf[qt][1], sb);
;           const unsigned mb = (mw[qt] >> (fq * 8)) & 0xFFu;
;           float pr[8];
; #pragma unroll
;           for (int i = 0; i < 4; ++i) {
;             float pa_ = __builtin_amdgcn_exp2f(sa[i] * sc2 - mref[qt]);
;             float pb_ = __builtin_amdgcn_exp2f(sb[i] * sc2 - mref[qt]);
;             pr[i] = ((mb >> i) & 1u) ? pa_ : 0.f;
;             pr[4 + i] = ((mb >> (4 + i)) & 1u) ? pb_ : 0.f;
;           }
;           lsum[qt] += ((pr[0] + pr[1]) + (pr[2] + pr[3])) + ((pr[4] + pr[5]) + (pr[6] + pr[7]));
;           union { unsigned u[4]; bf16x8 v; } pk;
;           pk.u[0] = pack2(pr[0], pr[1]); pk.u[1] = pack2(pr[2], pr[3]); pk.u[2] = pack2(pr[4], pr[5]); pk.u[3] = pack2(pr[6], pr[7]);
; #pragma unroll
;           for (int dt = 0; dt < 4; ++dt) o[qt][dt] = MFMA16(vf[dt], pk.v, o[qt][dt]);
;         }
;       }
.LBB0_4853:
	s_ashr_i32 s1, s0, 31
	v_lshl_add_u64 v[126:127], s[0:1], 1, v[102:103]
	v_lshl_add_u64 v[136:137], v[114:115], 0, s[36:37]
	s_mov_b32 s1, 0x187a1000
	v_add_co_u32_e32 v132, vcc, s1, v136
	s_mov_b32 s1, 0x187a0000
	s_nop 0
	v_addc_co_u32_e32 v133, vcc, 0, v137, vcc
	v_add_co_u32_e32 v140, vcc, s1, v136
	global_load_dwordx4 v[122:125], v[132:133], off offset:3136
	s_nop 0
	global_load_dwordx4 v[132:135], v[132:133], off offset:3072
	v_addc_co_u32_e32 v141, vcc, 0, v137, vcc
	global_load_dwordx4 v[136:139], v[140:141], off offset:3136
	s_nop 0
	global_load_dwordx4 v[140:143], v[140:141], off offset:3072
	v_lshl_add_u64 v[144:145], v[106:107], 0, s[36:37]
	global_load_dword v156, v[144:145], off
	v_lshl_add_u64 v[144:145], v[108:109], 0, s[36:37]
	global_load_dword v157, v[144:145], off
	s_mov_b32 s1, 0x10000
	v_add_co_u32_e32 v148, vcc, s1, v126
	s_mov_b32 s1, 0x21000
	s_nop 0
	v_addc_co_u32_e32 v149, vcc, 0, v127, vcc
	v_lshl_add_u64 v[144:145], v[110:111], 0, s[36:37]
	v_add_co_u32_e32 v152, vcc, s1, v126
	global_load_dword v159, v[144:145], off
	v_lshl_add_u64 v[144:145], v[112:113], 0, s[36:37]
	v_addc_co_u32_e32 v153, vcc, 0, v127, vcc
	s_mov_b32 s1, 0x31000
	global_load_dword v202, v[144:145], off
	s_nop 0
	global_load_dwordx4 v[144:147], v[126:127], off
	v_add_co_u32_e32 v126, vcc, s1, v126
	global_load_dwordx4 v[148:151], v[148:149], off offset:2048
	s_nop 0
	v_addc_co_u32_e32 v127, vcc, 0, v127, vcc
	global_load_dwordx4 v[152:155], v[152:153], off
	s_add_i32 s8, s8, 4
	global_load_dwordx4 v[180:183], v[126:127], off offset:2048
	s_addk_i32 s0, 0x80
	v_lshl_add_u64 v[106:107], v[106:107], 0, 16
	v_lshl_add_u64 v[108:109], v[108:109], 0, 16
	v_lshl_add_u64 v[110:111], v[110:111], 0, 16
	v_lshl_add_u64 v[112:113], v[112:113], 0, 16
	v_lshl_add_u64 v[114:115], v[114:115], 0, s[22:23]
	s_cmp_lt_i32 s8, 62
	s_waitcnt vmcnt(10)
	v_mfma_f32_16x16x32_bf16 v[188:191], v[132:135], v[8:11], 0
	s_waitcnt vmcnt(7)
	v_lshrrev_b32_e32 v204, v98, v156
	v_mfma_f32_16x16x32_bf16 v[184:187], v[140:143], v[8:11], 0
	s_waitcnt vmcnt(6)
	v_lshrrev_b32_e32 v203, v97, v157
	v_bfe_i32 v208, v203, 0, 1
	v_bfe_i32 v209, v204, 0, 1
	v_mfma_f32_16x16x32_bf16 v[188:191], v[122:125], v[16:19], v[188:191]
	v_bfe_i32 v210, v203, 1, 1
	s_waitcnt vmcnt(5)
	v_lshrrev_b32_e32 v159, v98, v159
	v_mfma_f32_16x16x32_bf16 v[184:187], v[136:139], v[16:19], v[184:187]
	s_nop 2
	v_fma_f32 v127, v188, s33, -v118
	v_exp_f32_e32 v192, v127
	s_nop 2
	v_fma_f32 v127, v185, s33, -v118
	v_exp_f32_e32 v193, v127
	v_fma_f32 v127, v189, s33, -v118
	v_exp_f32_e32 v194, v127
	v_fma_f32 v127, v186, s33, -v118
	v_exp_f32_e32 v195, v127
	v_fma_f32 v127, v190, s33, -v118
	v_fma_f32 v126, v184, s33, -v118
	v_exp_f32_e32 v196, v127
	v_fma_f32 v127, v187, s33, -v118
	v_mfma_f32_16x16x32_bf16 v[184:187], v[140:143], v[28:31], 0
	v_exp_f32_e32 v197, v127
	v_fma_f32 v127, v191, s33, -v118
	v_exp_f32_e32 v198, v127
	v_mfma_f32_16x16x32_bf16 v[188:191], v[132:135], v[28:31], 0
	v_exp_f32_e32 v126, v126
	v_mfma_f32_16x16x32_bf16 v[184:187], v[136:139], v[32:35], v[184:187]
	v_mfma_f32_16x16x32_bf16 v[188:191], v[122:125], v[32:35], v[188:191]
	s_nop 6
	v_fma_f32 v127, v184, s33, -v119
	v_exp_f32_e32 v127, v127
	v_fma_f32 v185, v185, s33, -v119
	v_fma_f32 v184, v188, s33, -v119
	v_exp_f32_e32 v185, v185
	v_fma_f32 v188, v189, s33, -v119
	v_exp_f32_e32 v199, v188
	v_fma_f32 v186, v186, s33, -v119
	v_fma_f32 v188, v190, s33, -v119
	v_exp_f32_e32 v186, v186
	v_exp_f32_e32 v200, v188
	v_fma_f32 v188, v191, s33, -v119
	v_and_b32_e32 v127, v127, v208
	v_fma_f32 v187, v187, s33, -v119
	v_exp_f32_e32 v201, v188
	v_and_b32_e32 v126, v126, v209
	v_bfe_i32 v211, v204, 1, 1
	v_exp_f32_e32 v187, v187
	v_exp_f32_e32 v184, v184
	v_and_b32_e32 v157, v185, v210
	v_bfe_i32 v212, v203, 2, 1
	v_bfe_i32 v213, v204, 2, 1
	v_and_b32_e32 v156, v193, v211
	v_bfe_i32 v214, v203, 3, 1
	s_nop 0
	v_and_b32_e32 v189, v186, v212
	v_bfe_i32 v215, v204, 3, 1
	s_nop 0
	v_and_b32_e32 v188, v195, v213
	v_bfe_i32 v216, v203, 4, 1
	s_nop 0
	v_and_b32_e32 v191, v187, v214
	v_bfe_i32 v217, v204, 4, 1
	s_nop 0
	v_and_b32_e32 v190, v197, v215
	v_bfe_i32 v219, v204, 5, 1
	s_nop 0
	v_and_b32_e32 v193, v184, v216
	v_bfe_i32 v218, v203, 5, 1
	v_pk_add_f32 v[186:187], v[188:189], v[190:191]
	v_and_b32_e32 v192, v192, v217
	v_bfe_i32 v220, v203, 6, 1
	s_nop 0
	v_and_b32_e32 v195, v199, v218
	v_bfe_i32 v221, v204, 6, 1
	s_nop 0
	v_and_b32_e32 v194, v194, v219
	v_bfe_i32 v222, v203, 7, 1
	s_nop 0
	v_and_b32_e32 v197, v200, v220
	v_bfe_i32 v223, v204, 7, 1
	s_nop 0
	v_and_b32_e32 v196, v196, v221
	s_nop 1
	v_and_b32_e32 v199, v201, v222
	v_pk_add_f32 v[184:185], v[126:127], v[156:157]
	s_nop 0
	v_and_b32_e32 v198, v198, v223
	v_pk_add_f32 v[184:185], v[184:185], v[186:187]
	v_pk_add_f32 v[186:187], v[192:193], v[194:195]
	v_pk_add_f32 v[200:201], v[196:197], v[198:199]
	s_nop 0
	v_pk_add_f32 v[186:187], v[186:187], v[200:201]
	s_nop 0
	v_pk_add_f32 v[200:201], v[184:185], v[186:187]
	v_cvt_pk_bf16_f32 v184, v126, v156
	v_cvt_pk_bf16_f32 v185, v188, v190
	v_cvt_pk_bf16_f32 v186, v192, v194
	v_cvt_pk_bf16_f32 v187, v196, v198
	v_pk_add_f32 v[104:105], v[104:105], v[200:201]
	s_waitcnt vmcnt(3)
; #define MFMA16(a, b, c) __builtin_amdgcn_mfma_f32_16x16x32_bf16((a), (b), (c), 0, 0, 0)
; DI void attn_block(const Params& p, int isP, int sq, int c, int h) {
;     ...
;       for (int qt = 0; qt < 4; ++qt) {
;         if (qt < nqt) {
;           f32x4 sa = {0.f, 0.f, 0.f, 0.f}, sb = {0.f, 0.f, 0.f, 0.f};
;           sa = MFMA16(ka0, qf[qt][0], sa); sa = MFMA16(ka1, qf[qt][1], sa);
;           sb = MFMA16(kb0, qf[qt][0], sb); sb = MFMA16(kb1, qf[qt][1], sb);
;           const unsigned mb = (mw[qt] >> (fq * 8)) & 0xFFu;
;           float pr[8];
; #pragma unroll
;           for (int i = 0; i < 4; ++i) {
;             float pa_ = __builtin_amdgcn_exp2f(sa[i] * sc2 - mref[qt]);
;             float pb_ = __builtin_amdgcn_exp2f(sb[i] * sc2 - mref[qt]);
;             pr[i] = ((mb >> i) & 1u) ? pa_ : 0.f;
;             pr[4 + i] = ((mb >> (4 + i)) & 1u) ? pb_ : 0.f;
;           }
;           lsum[qt] += ((pr[0] + pr[1]) + (pr[2] + pr[3])) + ((pr[4] + pr[5]) + (pr[6] + pr[7]));
;           union { unsigned u[4]; bf16x8 v; } pk;
;           pk.u[0] = pack2(pr[0], pr[1]); pk.u[1] = pack2(pr[2], pr[3]); pk.u[2] = pack2(pr[4], pr[5]); pk.u[3] = pack2(pr[6], pr[7]);
; #pragma unroll
;           for (int dt = 0; dt < 4; ++dt) o[qt][dt] = MFMA16(vf[dt], pk.v, o[qt][dt]);
;         }
;       }
;       ka0 = nka0; ka1 = nka1; kb0 = nkb0; kb1 = nkb1;
; #pragma unroll
;       for (int dt = 0; dt < 4; ++dt) vf[dt] = nvf[dt];
; #pragma unroll
;       for (int qt = 0; qt < 4; ++qt) mw[qt] = nmw[qt];
;     }
	v_mfma_f32_16x16x32_bf16 v[64:67], v[144:147], v[184:187], v[64:67]
	s_waitcnt vmcnt(2)
	v_mfma_f32_16x16x32_bf16 v[92:95], v[148:151], v[184:187], v[92:95]
	s_waitcnt vmcnt(1)
	v_mfma_f32_16x16x32_bf16 v[88:91], v[152:155], v[184:187], v[88:91]
	s_waitcnt vmcnt(0)
	v_mfma_f32_16x16x32_bf16 v[84:87], v[180:183], v[184:187], v[84:87]
	v_cvt_pk_bf16_f32 v184, v127, v157
	v_cvt_pk_bf16_f32 v185, v189, v191
	v_cvt_pk_bf16_f32 v186, v193, v195
	v_cvt_pk_bf16_f32 v187, v197, v199
	v_mfma_f32_16x16x32_bf16 v[188:191], v[132:135], v[48:51], 0
	s_nop 0
	v_mfma_f32_16x16x32_bf16 v[80:83], v[144:147], v[184:187], v[80:83]
	v_mfma_f32_16x16x32_bf16 v[76:79], v[148:151], v[184:187], v[76:79]
	v_mfma_f32_16x16x32_bf16 v[72:75], v[152:155], v[184:187], v[72:75]
	v_mfma_f32_16x16x32_bf16 v[68:71], v[180:183], v[184:187], v[68:71]
	v_mfma_f32_16x16x32_bf16 v[184:187], v[140:143], v[48:51], 0
	v_mfma_f32_16x16x32_bf16 v[188:191], v[122:125], v[52:55], v[188:191]
	v_mfma_f32_16x16x32_bf16 v[184:187], v[136:139], v[52:55], v[184:187]
	v_mfma_f32_16x16x32_bf16 v[140:143], v[140:143], v[56:59], 0
	s_nop 5
	v_fma_f32 v127, v188, s33, -v120
	v_exp_f32_e32 v156, v127
	v_fma_f32 v127, v185, s33, -v120
	v_exp_f32_e32 v157, v127
	v_fma_f32 v127, v189, s33, -v120
	v_fma_f32 v126, v184, s33, -v120
	v_exp_f32_e32 v184, v127
	v_fma_f32 v127, v186, s33, -v120
	v_mfma_f32_16x16x32_bf16 v[136:139], v[136:139], v[60:63], v[140:143]
	v_exp_f32_e32 v185, v127
	v_fma_f32 v127, v190, s33, -v120
	v_exp_f32_e32 v186, v127
	v_mfma_f32_16x16x32_bf16 v[132:135], v[132:135], v[56:59], 0
	v_fma_f32 v127, v187, s33, -v120
	v_exp_f32_e32 v187, v127
	v_fma_f32 v127, v191, s33, -v120
	v_exp_f32_e32 v188, v127
	v_fma_f32 v127, v136, s33, -v121
	v_mfma_f32_16x16x32_bf16 v[122:125], v[122:125], v[60:63], v[132:135]
	v_exp_f32_e32 v127, v127
	v_exp_f32_e32 v126, v126
	v_lshrrev_b32_e32 v189, v97, v202
	v_fma_f32 v133, v138, s33, -v121
	v_fma_f32 v132, v137, s33, -v121
	v_exp_f32_e32 v134, v133
	v_fma_f32 v133, v139, s33, -v121
	v_exp_f32_e32 v132, v132
	v_exp_f32_e32 v136, v133
	v_bfe_i32 v208, v189, 0, 1
	v_bfe_i32 v209, v159, 0, 1
	v_bfe_i32 v210, v189, 1, 1
	v_fma_f32 v122, v122, s33, -v121
	v_and_b32_e32 v127, v127, v208
	v_bfe_i32 v211, v159, 1, 1
	v_bfe_i32 v213, v159, 2, 1
	v_and_b32_e32 v126, v126, v209
	v_exp_f32_e32 v122, v122
	v_fma_f32 v123, v123, s33, -v121
	v_and_b32_e32 v133, v132, v210
	v_bfe_i32 v212, v189, 2, 1
	v_bfe_i32 v215, v159, 3, 1
	v_and_b32_e32 v132, v157, v211
	v_exp_f32_e32 v123, v123
	v_fma_f32 v124, v124, s33, -v121
	v_and_b32_e32 v135, v134, v212
	v_bfe_i32 v214, v189, 3, 1
	v_bfe_i32 v217, v159, 4, 1
	v_and_b32_e32 v134, v185, v213
	v_exp_f32_e32 v124, v124
	v_fma_f32 v125, v125, s33, -v121
	v_and_b32_e32 v137, v136, v214
	v_bfe_i32 v216, v189, 4, 1
	v_exp_f32_e32 v125, v125
	v_and_b32_e32 v136, v187, v215
	s_nop 1
	v_and_b32_e32 v139, v122, v216
	v_bfe_i32 v218, v189, 5, 1
	v_bfe_i32 v219, v159, 5, 1
	v_and_b32_e32 v138, v156, v217
	v_bfe_i32 v220, v189, 6, 1
	s_nop 0
	v_and_b32_e32 v141, v123, v218
	v_bfe_i32 v221, v159, 6, 1
	s_nop 0
	v_and_b32_e32 v140, v184, v219
	v_bfe_i32 v222, v189, 7, 1
	s_nop 0
	v_and_b32_e32 v143, v124, v220
	v_bfe_i32 v223, v159, 7, 1
	s_nop 0
	v_and_b32_e32 v142, v186, v221
	s_nop 1
	v_and_b32_e32 v157, v125, v222
	v_pk_add_f32 v[122:123], v[126:127], v[132:133]
	v_pk_add_f32 v[124:125], v[134:135], v[136:137]
	v_and_b32_e32 v156, v188, v223
	v_pk_add_f32 v[122:123], v[122:123], v[124:125]
	v_pk_add_f32 v[124:125], v[138:139], v[140:141]
	v_pk_add_f32 v[184:185], v[142:143], v[156:157]
	s_nop 0
	v_pk_add_f32 v[124:125], v[124:125], v[184:185]
	s_nop 0
	v_pk_add_f32 v[184:185], v[122:123], v[124:125]
	v_cvt_pk_bf16_f32 v122, v126, v132
	v_cvt_pk_bf16_f32 v123, v134, v136
	v_cvt_pk_bf16_f32 v124, v138, v140
	v_cvt_pk_bf16_f32 v125, v142, v156
	v_pk_add_f32 v[100:101], v[100:101], v[184:185]
	s_nop 0
	v_mfma_f32_16x16x32_bf16 v[44:47], v[144:147], v[122:125], v[44:47]
	v_mfma_f32_16x16x32_bf16 v[40:43], v[148:151], v[122:125], v[40:43]
	v_mfma_f32_16x16x32_bf16 v[36:39], v[152:155], v[122:125], v[36:39]
	v_mfma_f32_16x16x32_bf16 v[24:27], v[180:183], v[122:125], v[24:27]
	v_cvt_pk_bf16_f32 v122, v127, v133
	v_cvt_pk_bf16_f32 v123, v135, v137
	v_cvt_pk_bf16_f32 v124, v139, v141
	v_cvt_pk_bf16_f32 v125, v143, v157
	s_nop 1
	v_mfma_f32_16x16x32_bf16 v[20:23], v[144:147], v[122:125], v[20:23]
	v_mfma_f32_16x16x32_bf16 v[12:15], v[148:151], v[122:125], v[12:15]
	v_mfma_f32_16x16x32_bf16 v[4:7], v[152:155], v[122:125], v[4:7]
	v_mfma_f32_16x16x32_bf16 v[0:3], v[180:183], v[122:125], v[0:3]
	s_cbranch_scc1 .LBB0_4853

; #define MFMA16(a, b, c) __builtin_amdgcn_mfma_f32_16x16x32_bf16((a), (b), (c), 0, 0, 0)
; DI void attn_block(const Params& p, int isP, int sq, int c, int h) {
;     ...
;     for (; s < nsteps; s += 4) {
;       const int sn = (s + 4 < nsteps) ? s + 4 : s;
;       const bfr* pa = kptr + (long)sn * 32 * 512;
;       const bf16x8 nka0 = *(const bf16x8*)pa, nka1 = *(const bf16x8*)(pa + 32);
;       const bf16x8 nkb0 = *(const bf16x8*)(pa + 4 * 512), nkb1 = *(const bf16x8*)(pa + 4 * 512 + 32);
;       bf16x8 nvf[4];
; #pragma unroll
;       for (int dt = 0; dt < 4; ++dt) nvf[dt] = *(const bf16x8*)(vptr + (long)dt * 16 * vld + sn * 32);
;       unsigned nmw[4];
; #pragma unroll
;       for (int qt = 0; qt < 4; ++qt) nmw[qt] = mrow[qt][sn];
; #pragma unroll
;       for (int qt = 0; qt < 4; ++qt) {
;         if (qt < nqt) {
;           f32x4 sa = {0.f, 0.f, 0.f, 0.f}, sb = {0.f, 0.f, 0.f, 0.f};
;           sa = MFMA16(ka0, qf[qt][0], sa); sa = MFMA16(ka1, qf[qt][1], sa);
;           sb = MFMA16(kb0, qf[qt][0], sb); sb = MFMA16(kb1, qf[qt][1], sb);
;           const unsigned mb = (mw[qt] >> (fq * 8)) & 0xFFu;
;           float pr[8];
; #pragma unroll
;           for (int i = 0; i < 4; ++i) {
;             float pa_ = __builtin_amdgcn_exp2f(sa[i] * sc2 - mref[qt]);
;             float pb_ = __builtin_amdgcn_exp2f(sb[i] * sc2 - mref[qt]);
;             pr[i] = ((mb >> i) & 1u) ? pa_ : 0.f;
;             pr[4 + i] = ((mb >> (4 + i)) & 1u) ? pb_ : 0.f;
;           }
;           lsum[qt] += ((pr[0] + pr[1]) + (pr[2] + pr[3])) + ((pr[4] + pr[5]) + (pr[6] + pr[7]));
;           union { unsigned u[4]; bf16x8 v; } pk;
;           pk.u[0] = pack2(pr[0], pr[1]); pk.u[1] = pack2(pr[2], pr[3]); pk.u[2] = pack2(pr[4], pr[5]); pk.u[3] = pack2(pr[6], pr[7]);
; #pragma unroll
;           for (int dt = 0; dt < 4; ++dt) o[qt][dt] = MFMA16(vf[dt], pk.v, o[qt][dt]);
;         }
;       }
.LBB0_4861:
	v_lshl_add_u64 v[96:97], v[156:157], 0, s[36:37]
	v_add_co_u32_e32 v98, vcc, s8, v96
	s_ashr_i32 s1, s0, 31
	s_nop 0
	v_addc_co_u32_e32 v99, vcc, 0, v97, vcc
	v_add_co_u32_e32 v96, vcc, s9, v96
	global_load_dwordx4 v[112:115], v[98:99], off offset:3136
	global_load_dwordx4 v[116:119], v[98:99], off offset:3072
	v_addc_co_u32_e32 v97, vcc, 0, v97, vcc
	global_load_dwordx4 v[120:123], v[96:97], off offset:3136
	global_load_dwordx4 v[124:127], v[96:97], off offset:3072
	v_lshl_add_u64 v[96:97], v[148:149], 0, s[36:37]
	global_load_dword v128, v[96:97], off
	v_lshl_add_u64 v[96:97], v[150:151], 0, s[36:37]
	global_load_dword v159, v[96:97], off
	v_lshl_add_u64 v[108:109], s[0:1], 1, v[144:145]
	s_mov_b32 s1, 0x20000
	v_add_co_u32_e32 v100, vcc, s1, v108
	s_mov_b32 s1, 0x40000
	s_nop 0
	v_addc_co_u32_e32 v101, vcc, 0, v109, vcc
	v_lshl_add_u64 v[96:97], v[152:153], 0, s[36:37]
	v_add_co_u32_e32 v104, vcc, s1, v108
	global_load_dword v185, v[96:97], off
	v_lshl_add_u64 v[96:97], v[154:155], 0, s[36:37]
	v_addc_co_u32_e32 v105, vcc, 0, v109, vcc
	s_mov_b32 s1, 0x60000
	global_load_dword v204, v[96:97], off
	s_add_i32 s7, s7, 4
	global_load_dwordx4 v[96:99], v[108:109], off
	v_add_co_u32_e32 v108, vcc, s1, v108
	global_load_dwordx4 v[100:103], v[100:101], off offset:1024
	s_nop 0
	v_addc_co_u32_e32 v109, vcc, 0, v109, vcc
	global_load_dwordx4 v[104:107], v[104:105], off offset:2048
	s_addk_i32 s0, 0x80
	global_load_dwordx4 v[108:111], v[108:109], off offset:3072
	v_lshl_add_u64 v[148:149], v[148:149], 0, 16
	v_lshl_add_u64 v[150:151], v[150:151], 0, 16
	v_lshl_add_u64 v[152:153], v[152:153], 0, 16
	v_lshl_add_u64 v[154:155], v[154:155], 0, 16
	v_lshl_add_u64 v[156:157], v[156:157], 0, s[22:23]
	s_cmp_le_i32 s7, s21
	s_waitcnt vmcnt(10)
	v_mfma_f32_16x16x32_bf16 v[186:189], v[116:119], v[16:19], 0
	s_waitcnt vmcnt(7)
	v_lshrrev_b32_e32 v128, v140, v128
	v_mfma_f32_16x16x32_bf16 v[132:135], v[124:127], v[16:19], 0
	s_waitcnt vmcnt(6)
	v_lshrrev_b32_e32 v159, v137, v159
	s_waitcnt vmcnt(5)
	v_lshrrev_b32_e32 v185, v140, v185
	v_mfma_f32_16x16x32_bf16 v[132:135], v[120:123], v[24:27], v[132:135]
	v_mfma_f32_16x16x32_bf16 v[186:189], v[112:115], v[24:27], v[186:189]
	s_nop 6
	v_fma_f32 v132, v132, s33, -v181
	v_exp_f32_e32 v190, v132
	v_fma_f32 v132, v186, s33, -v181
	v_exp_f32_e32 v194, v132
	v_fma_f32 v132, v133, s33, -v181
	v_exp_f32_e32 v191, v132
	v_fma_f32 v132, v187, s33, -v181
	v_exp_f32_e32 v196, v132
	v_fma_f32 v132, v134, s33, -v181
	v_exp_f32_e32 v192, v132
	v_fma_f32 v132, v188, s33, -v181
	v_exp_f32_e32 v198, v132
	v_fma_f32 v132, v135, s33, -v181
	v_exp_f32_e32 v195, v132
	v_fma_f32 v132, v189, s33, -v181
	v_mfma_f32_16x16x32_bf16 v[186:189], v[116:119], v[36:39], 0
	v_exp_f32_e32 v200, v132
	v_mfma_f32_16x16x32_bf16 v[132:135], v[124:127], v[36:39], 0
	v_mfma_f32_16x16x32_bf16 v[186:189], v[112:115], v[44:47], v[186:189]
	v_mfma_f32_16x16x32_bf16 v[132:135], v[120:123], v[44:47], v[132:135]
	s_nop 6
	v_fma_f32 v186, v186, s33, -v182
	v_fma_f32 v132, v132, s33, -v182
	v_exp_f32_e32 v197, v186
	v_fma_f32 v186, v187, s33, -v182
	v_exp_f32_e32 v132, v132
	v_exp_f32_e32 v199, v186
	v_fma_f32 v186, v188, s33, -v182
	v_fma_f32 v133, v133, s33, -v182
	v_exp_f32_e32 v201, v186
	v_fma_f32 v186, v189, s33, -v182
	v_exp_f32_e32 v133, v133
	v_exp_f32_e32 v202, v186
	v_bfe_i32 v208, v159, 0, 1
	v_fma_f32 v134, v134, s33, -v182
	v_bfe_i32 v209, v128, 0, 1
	v_exp_f32_e32 v134, v134
	v_fma_f32 v135, v135, s33, -v182
	v_and_b32_e32 v187, v132, v208
	v_bfe_i32 v210, v159, 1, 1
	v_bfe_i32 v211, v128, 1, 1
	v_and_b32_e32 v186, v190, v209
	v_exp_f32_e32 v135, v135
	v_bfe_i32 v212, v159, 2, 1
	v_and_b32_e32 v189, v133, v210
	v_bfe_i32 v213, v128, 2, 1
	s_nop 0
	v_and_b32_e32 v188, v191, v211
	v_bfe_i32 v214, v159, 3, 1
	s_nop 0
	v_and_b32_e32 v191, v134, v212
	v_bfe_i32 v215, v128, 3, 1
	s_nop 0
	v_and_b32_e32 v190, v192, v213
	v_bfe_i32 v216, v159, 4, 1
	s_nop 0
	v_and_b32_e32 v193, v135, v214
	v_bfe_i32 v217, v128, 4, 1
	s_nop 0
	v_and_b32_e32 v192, v195, v215
	v_bfe_i32 v218, v159, 5, 1
	v_pk_add_f32 v[134:135], v[190:191], v[192:193]
	v_and_b32_e32 v195, v197, v216
	v_bfe_i32 v219, v128, 5, 1
	s_nop 0
	v_and_b32_e32 v194, v194, v217
	v_bfe_i32 v220, v159, 6, 1
	s_nop 0
	v_and_b32_e32 v197, v199, v218
	v_bfe_i32 v221, v128, 6, 1
	v_bfe_i32 v223, v128, 7, 1
	v_and_b32_e32 v196, v196, v219
	v_bfe_i32 v222, v159, 7, 1
	s_nop 0
	v_and_b32_e32 v199, v201, v220
	s_nop 1
	v_and_b32_e32 v198, v198, v221
	v_pk_add_f32 v[132:133], v[186:187], v[188:189]
	s_nop 0
	v_and_b32_e32 v201, v202, v222
	v_pk_add_f32 v[132:133], v[132:133], v[134:135]
	v_pk_add_f32 v[134:135], v[194:195], v[196:197]
	v_and_b32_e32 v200, v200, v223
	v_pk_add_f32 v[202:203], v[198:199], v[200:201]
	s_nop 0
	v_pk_add_f32 v[134:135], v[134:135], v[202:203]
	s_nop 0
	v_pk_add_f32 v[202:203], v[132:133], v[134:135]
	v_cvt_pk_bf16_f32 v132, v186, v188
	v_cvt_pk_bf16_f32 v133, v190, v192
	v_cvt_pk_bf16_f32 v134, v194, v196
	v_cvt_pk_bf16_f32 v135, v198, v200
	v_pk_add_f32 v[146:147], v[146:147], v[202:203]
	s_waitcnt vmcnt(3)
	v_mfma_f32_16x16x32_bf16 v[64:67], v[96:99], v[132:135], v[64:67]
	s_waitcnt vmcnt(2)
	v_mfma_f32_16x16x32_bf16 v[92:95], v[100:103], v[132:135], v[92:95]
	s_waitcnt vmcnt(1)
	v_mfma_f32_16x16x32_bf16 v[88:91], v[104:107], v[132:135], v[88:91]
	s_waitcnt vmcnt(0)
; #define MFMA16(a, b, c) __builtin_amdgcn_mfma_f32_16x16x32_bf16((a), (b), (c), 0, 0, 0)
; DI void attn_block(const Params& p, int isP, int sq, int c, int h) {
;     ...
;       for (int qt = 0; qt < 4; ++qt) {
;         if (qt < nqt) {
;           f32x4 sa = {0.f, 0.f, 0.f, 0.f}, sb = {0.f, 0.f, 0.f, 0.f};
;           sa = MFMA16(ka0, qf[qt][0], sa); sa = MFMA16(ka1, qf[qt][1], sa);
;           sb = MFMA16(kb0, qf[qt][0], sb); sb = MFMA16(kb1, qf[qt][1], sb);
;           const unsigned mb = (mw[qt] >> (fq * 8)) & 0xFFu;
;           float pr[8];
; #pragma unroll
;           for (int i = 0; i < 4; ++i) {
;             float pa_ = __builtin_amdgcn_exp2f(sa[i] * sc2 - mref[qt]);
;             float pb_ = __builtin_amdgcn_exp2f(sb[i] * sc2 - mref[qt]);
;             pr[i] = ((mb >> i) & 1u) ? pa_ : 0.f;
;             pr[4 + i] = ((mb >> (4 + i)) & 1u) ? pb_ : 0.f;
;           }
;           lsum[qt] += ((pr[0] + pr[1]) + (pr[2] + pr[3])) + ((pr[4] + pr[5]) + (pr[6] + pr[7]));
;           union { unsigned u[4]; bf16x8 v; } pk;
;           pk.u[0] = pack2(pr[0], pr[1]); pk.u[1] = pack2(pr[2], pr[3]); pk.u[2] = pack2(pr[4], pr[5]); pk.u[3] = pack2(pr[6], pr[7]);
; #pragma unroll
;           for (int dt = 0; dt < 4; ++dt) o[qt][dt] = MFMA16(vf[dt], pk.v, o[qt][dt]);
;         }
;       }
;       ka0 = nka0; ka1 = nka1; kb0 = nkb0; kb1 = nkb1;
; #pragma unroll
;       for (int dt = 0; dt < 4; ++dt) vf[dt] = nvf[dt];
; #pragma unroll
;       for (int qt = 0; qt < 4; ++qt) mw[qt] = nmw[qt];
;     }
	v_mfma_f32_16x16x32_bf16 v[84:87], v[108:111], v[132:135], v[84:87]
	v_cvt_pk_bf16_f32 v132, v187, v189
	v_cvt_pk_bf16_f32 v133, v191, v193
	v_cvt_pk_bf16_f32 v134, v195, v197
	v_cvt_pk_bf16_f32 v135, v199, v201
	v_mfma_f32_16x16x32_bf16 v[186:189], v[116:119], v[48:51], 0
	s_nop 0
	v_mfma_f32_16x16x32_bf16 v[80:83], v[96:99], v[132:135], v[80:83]
	v_mfma_f32_16x16x32_bf16 v[76:79], v[100:103], v[132:135], v[76:79]
	v_mfma_f32_16x16x32_bf16 v[72:75], v[104:107], v[132:135], v[72:75]
	v_mfma_f32_16x16x32_bf16 v[68:71], v[108:111], v[132:135], v[68:71]
	v_mfma_f32_16x16x32_bf16 v[132:135], v[124:127], v[48:51], 0
	v_mfma_f32_16x16x32_bf16 v[124:127], v[124:127], v[56:59], 0
	v_mfma_f32_16x16x32_bf16 v[132:135], v[120:123], v[52:55], v[132:135]
	v_mfma_f32_16x16x32_bf16 v[120:123], v[120:123], v[60:63], v[124:127]
	v_mfma_f32_16x16x32_bf16 v[116:119], v[116:119], v[56:59], 0
	s_nop 5
	v_fma_f32 v128, v132, s33, -v183
	v_exp_f32_e32 v128, v128
	v_fma_f32 v133, v133, s33, -v183
	v_mfma_f32_16x16x32_bf16 v[186:189], v[112:115], v[52:55], v[186:189]
	v_exp_f32_e32 v133, v133
	v_fma_f32 v134, v134, s33, -v183
	v_exp_f32_e32 v134, v134
	v_mfma_f32_16x16x32_bf16 v[112:115], v[112:115], v[60:63], v[116:119]
	v_fma_f32 v135, v135, s33, -v183
	s_nop 2
	v_fma_f32 v132, v186, s33, -v183
	v_fma_f32 v186, v188, s33, -v183
	v_fma_f32 v116, v120, s33, -v184
	v_fma_f32 v117, v121, s33, -v184
	v_exp_f32_e32 v116, v116
	v_exp_f32_e32 v118, v117
	v_fma_f32 v117, v122, s33, -v184
	v_exp_f32_e32 v120, v117
	v_fma_f32 v117, v123, s33, -v184
	v_lshrrev_b32_e32 v188, v137, v204
	v_exp_f32_e32 v122, v117
	v_bfe_i32 v208, v188, 0, 1
	v_bfe_i32 v209, v185, 0, 1
	v_bfe_i32 v211, v185, 1, 1
	v_exp_f32_e32 v135, v135
	v_and_b32_e32 v117, v116, v208
	v_bfe_i32 v210, v188, 1, 1
	v_fma_f32 v112, v112, s33, -v184
	v_and_b32_e32 v116, v128, v209
	v_bfe_i32 v213, v185, 2, 1
	v_exp_f32_e32 v112, v112
	v_and_b32_e32 v119, v118, v210
	v_bfe_i32 v212, v188, 2, 1
	v_exp_f32_e32 v132, v132
	v_and_b32_e32 v118, v133, v211
	v_fma_f32 v113, v113, s33, -v184
	v_bfe_i32 v215, v185, 3, 1
	v_and_b32_e32 v121, v120, v212
	v_bfe_i32 v214, v188, 3, 1
	v_fma_f32 v159, v187, s33, -v183
	v_and_b32_e32 v120, v134, v213
	v_exp_f32_e32 v113, v113
	v_exp_f32_e32 v159, v159
	v_and_b32_e32 v123, v122, v214
	v_bfe_i32 v216, v188, 4, 1
	v_fma_f32 v114, v114, s33, -v184
	v_and_b32_e32 v122, v135, v215
	v_bfe_i32 v217, v185, 4, 1
	v_exp_f32_e32 v114, v114
	v_exp_f32_e32 v186, v186
	v_and_b32_e32 v125, v112, v216
	v_bfe_i32 v218, v188, 5, 1
	v_fma_f32 v115, v115, s33, -v184
	v_and_b32_e32 v124, v132, v217
	v_bfe_i32 v219, v185, 5, 1
	v_fma_f32 v187, v189, s33, -v183
	v_exp_f32_e32 v115, v115
	v_and_b32_e32 v127, v113, v218
	v_bfe_i32 v220, v188, 6, 1
	v_exp_f32_e32 v187, v187
	v_and_b32_e32 v126, v159, v219
	v_bfe_i32 v221, v185, 6, 1
	v_bfe_i32 v222, v188, 7, 1
	s_nop 0
	v_and_b32_e32 v133, v114, v220
	v_bfe_i32 v223, v185, 7, 1
	s_nop 0
	v_and_b32_e32 v132, v186, v221
	s_nop 1
	v_and_b32_e32 v135, v115, v222
	v_pk_add_f32 v[112:113], v[116:117], v[118:119]
	v_pk_add_f32 v[114:115], v[120:121], v[122:123]
	v_and_b32_e32 v134, v187, v223
	v_pk_add_f32 v[112:113], v[112:113], v[114:115]
	v_pk_add_f32 v[114:115], v[124:125], v[126:127]
	v_pk_add_f32 v[186:187], v[132:133], v[134:135]
	s_nop 0
	v_pk_add_f32 v[114:115], v[114:115], v[186:187]
	s_nop 0
	v_pk_add_f32 v[186:187], v[112:113], v[114:115]
	v_cvt_pk_bf16_f32 v112, v116, v118
	v_cvt_pk_bf16_f32 v113, v120, v122
	v_cvt_pk_bf16_f32 v114, v124, v126
	v_cvt_pk_bf16_f32 v115, v132, v134
	v_pk_add_f32 v[142:143], v[142:143], v[186:187]
	s_nop 0
	v_mfma_f32_16x16x32_bf16 v[40:43], v[96:99], v[112:115], v[40:43]
	v_mfma_f32_16x16x32_bf16 v[32:35], v[100:103], v[112:115], v[32:35]
	v_mfma_f32_16x16x32_bf16 v[28:31], v[104:107], v[112:115], v[28:31]
	v_mfma_f32_16x16x32_bf16 v[20:23], v[108:111], v[112:115], v[20:23]
	v_cvt_pk_bf16_f32 v112, v117, v119
	v_cvt_pk_bf16_f32 v113, v121, v123
	v_cvt_pk_bf16_f32 v114, v125, v127
	v_cvt_pk_bf16_f32 v115, v133, v135
	s_nop 1
	v_mfma_f32_16x16x32_bf16 v[12:15], v[96:99], v[112:115], v[12:15]
	v_mfma_f32_16x16x32_bf16 v[8:11], v[100:103], v[112:115], v[8:11]
	v_mfma_f32_16x16x32_bf16 v[4:7], v[104:107], v[112:115], v[4:7]
	v_mfma_f32_16x16x32_bf16 v[0:3], v[108:111], v[112:115], v[0:3]
	s_cbranch_scc1 .LBB0_4861
; DI void attn_block(const Params& p, int isP, int sq, int c, int h) {
;     ...
;   float* OS = (float*)smem;
;   float* LS = OS + 4 * 2048;
;   bfr* gay = (bfr*)(p.ws + W_GA);
; #pragma unroll
;   for (int rd = 0; rd < 2; ++rd) {
;     __syncthreads();
; #pragma unroll
;     for (int q2 = 0; q2 < 2; ++q2) {
;       const int qt = rd * 2 + q2;
;       float l = lsum[qt];
;       l += __shfl_xor(l, 16);
;       l += __shfl_xor(l, 32);
;       LS[(wid * 2 + q2) * 64 + lane] = l;
; #pragma unroll
;       for (int dt = 0; dt < 4; ++dt)
; #pragma unroll
;         for (int j = 0; j < 4; ++j) OS[((wid * 2 + q2) * 16 + dt * 4 + j) * 64 + lane] = o[qt][dt][j];
;     }
;     __syncthreads();
;     const int q2 = wid >> 1, qt = rd * 2 + q2;
;     if (qt < nqt) {
;       float l = 0.f;
; #pragma unroll
;       for (int w = 0; w < 4; ++w) l += LS[(w * 2 + q2) * 64 + lane];
;       const float inv = l > 0.f ? 1.f / l : 0.f;
;       const long rowoff = (long)(qrow0 + qt * 16 + fr) * 512 + h * 64;
; #pragma unroll
;       for (int d2 = 0; d2 < 2; ++d2) {
;         const int dt = (wid & 1) * 2 + d2;
;         float acc4[4];
; #pragma unroll
;         for (int j = 0; j < 4; ++j) {
;           float a = 0.f;
; #pragma unroll
;           for (int w = 0; w < 4; ++w) a += OS[((w * 2 + q2) * 16 + dt * 4 + j) * 64 + lane];
;           acc4[j] = a * inv;
;         }
;         uint2* ptr = (uint2*)(gay + rowoff + dt * 16 + fq * 4);
;         uint2 gv = *ptr;
;         float g0 = __uint_as_float(gv.x << 16), g1 = __uint_as_float(gv.x & 0xFFFF0000u);
;         float g2 = __uint_as_float(gv.y << 16), g3 = __uint_as_float(gv.y & 0xFFFF0000u);
;         uint2 ov;
;         ov.x = pack2(acc4[0] * g0, acc4[1] * g1);
;         ov.y = pack2(acc4[2] * g2, acc4[3] * g3);
;         *ptr = ov;
.LBB0_4862:
	s_and_saveexec_b64 s[0:1], s[96:97]
	v_mov_b32_e32 v131, 1
	v_mov_b32_e32 v130, 1
	global_atomic_add v130, v129, v130, s[38:39] offset:8 sc0
	s_or_b64 exec, exec, s[0:1]
	v_and_b32_e32 v16, 63, v141
	v_lshl_add_u32 v50, v16, 2, v169
	ds_bpermute_b32 v16, v180, v146
	s_lshl_b32 s9, s6, 1
	s_ashr_i32 s8, s19, 7
	s_add_u32 s0, s14, s20
	s_addc_u32 s1, s15, 0
	s_waitcnt lgkmcnt(0)
	v_add_f32_e32 v16, v146, v16
	ds_bpermute_b32 v17, v139, v16
	v_mov_b32_e32 v141, v129
	v_lshl_add_u64 v[48:49], s[0:1], 0, v[140:141]
	s_and_b32 s90, s9, 2
	s_lshl_b32 s90, s90, 5
	v_lshl_add_u32 v194, s8, 4, v138
	v_lshl_add_u32 v198, s8, 4, v136
	v_ashrrev_i32_e32 v195, 31, v194
	v_ashrrev_i32_e32 v199, 31, v198
	v_lshlrev_b64 v[194:195], 10, v[194:195]
	v_lshlrev_b64 v[198:199], 10, v[198:199]
	v_lshl_add_u64 v[194:195], v[48:49], 0, v[194:195]
	v_lshl_add_u64 v[198:199], v[48:49], 0, v[198:199]
	v_lshl_add_u64 v[194:195], v[194:195], 0, s[90:91]
	v_lshl_add_u64 v[198:199], v[198:199], 0, s[90:91]
	global_load_dwordx2 v[186:187], v[194:195], off
	global_load_dwordx2 v[188:189], v[194:195], off offset:32
	global_load_dwordx2 v[190:191], v[198:199], off
	global_load_dwordx2 v[192:193], v[198:199], off offset:32
	s_lshl_b32 s0, s6, 9
	v_add_u32_e32 v46, s0, v50
	s_waitcnt lgkmcnt(0)
	v_add_f32_e32 v16, v16, v17
	s_barrier
	ds_write_b32 v46, v16 offset:32768
	ds_bpermute_b32 v16, v180, v147
	s_lshl_b32 s0, s6, 13
	v_add_u32_e32 v17, s0, v50
	s_or_b32 s0, s9, 1
	s_lshl_b32 s18, s8, 8
	s_waitcnt lgkmcnt(0)
	v_add_f32_e32 v16, v147, v16
	ds_bpermute_b32 v18, v139, v16
	s_and_b32 s7, s9, 2
	s_lshl_b32 s1, s0, 8
	s_lshl_b32 s0, s0, 12
	v_add_u32_e32 v52, s1, v50
	s_waitcnt lgkmcnt(0)
	v_add_f32_e32 v16, v16, v18
	v_add_u32_e32 v51, s0, v50
	s_cmp_gt_i32 s8, 3
	v_add_u32_e32 v47, s18, v50
	ds_write2st64_b32 v17, v64, v65 offset1:1
	ds_write2st64_b32 v17, v66, v67 offset0:2 offset1:3
	ds_write2st64_b32 v17, v92, v93 offset0:4 offset1:5
	ds_write2st64_b32 v17, v94, v95 offset0:6 offset1:7
	ds_write2st64_b32 v17, v88, v89 offset0:8 offset1:9
	ds_write2st64_b32 v17, v90, v91 offset0:10 offset1:11
	ds_write2st64_b32 v17, v84, v85 offset0:12 offset1:13
	ds_write2st64_b32 v17, v86, v87 offset0:14 offset1:15
	ds_write_b32 v52, v16 offset:32768
	ds_write2st64_b32 v51, v80, v81 offset1:1
	ds_write2st64_b32 v51, v82, v83 offset0:2 offset1:3
	ds_write2st64_b32 v51, v76, v77 offset0:4 offset1:5
	ds_write2st64_b32 v51, v78, v79 offset0:6 offset1:7
	ds_write2st64_b32 v51, v72, v73 offset0:8 offset1:9
	ds_write2st64_b32 v51, v74, v75 offset0:10 offset1:11
	ds_write2st64_b32 v51, v68, v69 offset0:12 offset1:13
	ds_write2st64_b32 v51, v70, v71 offset0:14 offset1:15
	s_waitcnt lgkmcnt(0)
	s_barrier
	s_cbranch_scc1 .LBB0_4864
	ds_read2st64_b32 v[18:19], v47 offset0:128 offset1:130
	s_lshl_b32 s90, s7, 5
	s_waitcnt lgkmcnt(0)
	v_add_f32_e32 v16, 0, v18
	v_add_f32_e32 v16, v16, v19
	ds_read2st64_b32 v[18:19], v47 offset0:132 offset1:134
	s_waitcnt lgkmcnt(0)
	v_add_f32_e32 v16, v16, v18
	v_add_f32_e32 v16, v16, v19
	v_div_scale_f32 v18, s[18:19], v16, v16, 1.0
	v_rcp_f32_e32 v19, v18
	v_cmp_lt_f32_e64 s[0:1], 0, v16
	v_fma_f32 v24, -v18, v19, 1.0
	v_fmac_f32_e32 v19, v24, v19
	v_div_scale_f32 v24, vcc, 1.0, v16, 1.0
	v_mul_f32_e32 v25, v24, v19
	v_fma_f32 v26, -v18, v25, v24
	v_fmac_f32_e32 v25, v26, v19
	v_fma_f32 v18, -v18, v25, v24
	v_div_fmas_f32 v18, v18, v19, v25
	v_div_fixup_f32 v16, v18, v16, 1.0
	v_lshl_add_u32 v18, s8, 4, v138
	v_ashrrev_i32_e32 v19, 31, v18
	v_cndmask_b32_e64 v16, 0, v16, s[0:1]
	v_lshlrev_b64 v[18:19], 10, v[18:19]
	s_lshl_b32 s1, s7, 10
	s_lshl_b32 s0, s8, 12
	v_lshl_add_u64 v[24:25], v[48:49], 0, v[18:19]
	s_or_b32 s1, s1, s0
	v_add_u32_e32 v53, s1, v50
	v_lshl_add_u64 v[60:61], v[24:25], 0, s[90:91]
	ds_read2st64_b32 v[18:19], v53 offset1:1
	ds_read2st64_b32 v[26:27], v53 offset0:32 offset1:33
	ds_read2st64_b32 v[36:37], v53 offset0:64 offset1:65
	ds_read2st64_b32 v[38:39], v53 offset0:96 offset1:97
	ds_read2st64_b32 v[44:45], v53 offset0:2 offset1:3
	ds_read2st64_b32 v[54:55], v53 offset0:34 offset1:35
	ds_read2st64_b32 v[56:57], v53 offset0:66 offset1:67
	ds_read2st64_b32 v[58:59], v53 offset0:98 offset1:99
	s_waitcnt lgkmcnt(7)
	v_pk_add_f32 v[18:19], v[18:19], 0 op_sel_hi:[1,0]
	s_or_b32 s1, s7, 1
	s_waitcnt lgkmcnt(6)
	v_pk_add_f32 v[18:19], v[18:19], v[26:27]
	s_waitcnt lgkmcnt(3)
	v_pk_add_f32 v[26:27], v[44:45], 0 op_sel_hi:[1,0]
	v_pk_add_f32 v[18:19], v[18:19], v[36:37]
	s_waitcnt lgkmcnt(2)
	v_pk_add_f32 v[26:27], v[26:27], v[54:55]
	v_pk_add_f32 v[18:19], v[18:19], v[38:39]
	s_waitcnt lgkmcnt(1)
	v_pk_add_f32 v[26:27], v[26:27], v[56:57]
	v_pk_mul_f32 v[18:19], v[16:17], v[18:19] op_sel_hi:[0,1]
	s_waitcnt lgkmcnt(0)
	v_pk_add_f32 v[26:27], v[26:27], v[58:59]
	s_lshl_b32 s6, s1, 10
	v_pk_mul_f32 v[26:27], v[16:17], v[26:27] op_sel_hi:[0,1]
	s_or_b32 s0, s6, s0
	s_lshl_b32 s90, s1, 5
	v_lshl_add_u64 v[24:25], v[24:25], 0, s[90:91]
	s_waitcnt vmcnt(0)
	v_lshlrev_b32_e32 v64, 16, v186
	v_and_b32_e32 v65, 0xffff0000, v186
	v_lshlrev_b32_e32 v62, 16, v187
	v_and_b32_e32 v63, 0xffff0000, v187
	v_pk_mul_f32 v[18:19], v[18:19], v[64:65]
	v_pk_mul_f32 v[26:27], v[26:27], v[62:63]
	v_cvt_pk_bf16_f32 v18, v18, v19
	v_cvt_pk_bf16_f32 v19, v26, v27
	global_store_dwordx2 v[60:61], v[18:19], off
	v_add_u32_e32 v18, s0, v50
	ds_read2st64_b32 v[54:55], v18 offset1:1
	ds_read2st64_b32 v[56:57], v18 offset0:32 offset1:33
	ds_read2st64_b32 v[58:59], v18 offset0:64 offset1:65
	ds_read2st64_b32 v[60:61], v18 offset0:96 offset1:97
	ds_read2st64_b32 v[44:45], v18 offset0:2 offset1:3
	ds_read2st64_b32 v[38:39], v18 offset0:34 offset1:35
	ds_read2st64_b32 v[36:37], v18 offset0:66 offset1:67
	ds_read2st64_b32 v[18:19], v18 offset0:98 offset1:99
	s_waitcnt lgkmcnt(7)
	v_pk_add_f32 v[54:55], v[54:55], 0 op_sel_hi:[1,0]
	s_waitcnt lgkmcnt(3)
	v_pk_add_f32 v[44:45], v[44:45], 0 op_sel_hi:[1,0]
	v_pk_add_f32 v[54:55], v[54:55], v[56:57]
	s_waitcnt lgkmcnt(2)
	v_pk_add_f32 v[38:39], v[44:45], v[38:39]
	v_pk_add_f32 v[54:55], v[54:55], v[58:59]
	s_waitcnt lgkmcnt(1)
	v_pk_add_f32 v[36:37], v[38:39], v[36:37]
	v_pk_add_f32 v[54:55], v[54:55], v[60:61]
	s_waitcnt lgkmcnt(0)
	v_pk_add_f32 v[18:19], v[36:37], v[18:19]
	v_pk_mul_f32 v[54:55], v[16:17], v[54:55] op_sel_hi:[0,1]
	v_pk_mul_f32 v[18:19], v[16:17], v[18:19] op_sel_hi:[0,1]
	v_lshlrev_b32_e32 v62, 16, v188
	v_and_b32_e32 v63, 0xffff0000, v188
	v_lshlrev_b32_e32 v26, 16, v189
	v_and_b32_e32 v27, 0xffff0000, v189
	v_pk_mul_f32 v[54:55], v[54:55], v[62:63]
	v_pk_mul_f32 v[18:19], v[18:19], v[26:27]
	v_cvt_pk_bf16_f32 v54, v54, v55
	v_cvt_pk_bf16_f32 v55, v18, v19
	global_store_dwordx2 v[24:25], v[54:55], off

; __device__ __forceinline__ void xcd_barrier(const XcdBarrier& b) {
;     asm volatile("s_waitcnt vmcnt(0)" ::: "memory");
;     __syncthreads();
;     if (threadIdx.x == 0) {
;         unsigned* bar = b.bar;
;         __builtin_amdgcn_s_waitcnt(0);
;         unsigned nloc = b.st[0], nx = b.st[1];
;         if (nloc == 0u) { xcd_barrier_complete(bar, b.x, nloc, nx); b.st[0] = nloc; b.st[1] = nx; }
.LBB0_4868:
	s_waitcnt vmcnt(0)
	v_mov_b32_e32 v130, 0x800
	s_barrier
	s_and_saveexec_b64 s[0:1], s[96:97]
	s_cbranch_execz .LBB0_4920
	s_waitcnt vmcnt(0) expcnt(0) lgkmcnt(0)
	ds_read_b32 v2, v129 offset:16
	ds_read_b32 v0, v129 offset:20
	s_waitcnt lgkmcnt(1)
	v_cmp_ne_u32_e32 vcc, 0, v2
	s_cbranch_vccnz .LBB0_4884
	s_mov_b32 s8, 1
	s_branch .LBB0_4872
